# conv: per-token loads software-pipelined one iteration ahead (spare registers + copy), on top of prep_item prefetch
# speedup vs baseline: 1.0042x; 1.0042x over previous
; __device__ void phase_conv(const Params& p, int l, int nrows) {
;     ...
;         const bf16_t* gp = Gup + (size_t)tok0 * FF + f0;
;         u32x4 L[3], M[3], R[3];
;         { const bool v = c0 > 0;
;           L[0] = (v && up) ? *(const u32x4*)(gp - (size_t)65 * FF) : zero; L[1] = v ? *(const u32x4*)(gp - (size_t)FF) : zero; L[2] = (v && dn) ? *(const u32x4*)(gp + (size_t)63 * FF) : zero; }
;         M[0] = up ? *(const u32x4*)(gp - (size_t)64 * FF) : zero; M[1] = *(const u32x4*)gp; M[2] = dn ? *(const u32x4*)(gp + (size_t)64 * FF) : zero;
; #pragma unroll 8
;         for (int i = 0; i < 16; ++i) {
;             const bf16_t* np = gp + (size_t)(i + 1) * FF;
;             const bool v = (c0 + i + 1) < W;
;             R[0] = (v && up) ? *(const u32x4*)(np - (size_t)64 * FF) : zero; R[1] = v ? *(const u32x4*)np : zero; R[2] = (v && dn) ? *(const u32x4*)(np + (size_t)64 * FF) : zero;
.LBB0_716:
	s_or_b64 exec, exec, s[0:1]
	v_mad_i64_i32 v[108:109], s[0:1], v110, s81, 0
	v_lshl_add_u64 v[10:11], v[10:11], 1, v[108:109]
	v_add_u32_e32 v188, 8, v9
	v_mov_b32_e32 v192, v10
	v_lshl_add_u64 v[122:123], s[62:63], 0, v[10:11]
	s_mov_b64 s[88:89], 0
	s_mov_b64 s[20:21], s[62:63]
	v_add_u32_e32 v214, -7, v188
	v_cmp_lt_u32_e64 s[98:99], v214, v187
	s_add_u32 s100, s20, 0x7fad000
	s_addc_u32 s101, s21, 0
	global_load_dwordx4 v[196:199], v192, s[100:101] nt
	v_mov_b32_e32 v200, 0
	v_mov_b32_e32 v201, 0
	v_mov_b32_e32 v202, 0
	v_mov_b32_e32 v203, 0
	v_mov_b32_e32 v204, 0
	v_mov_b32_e32 v205, 0
	v_mov_b32_e32 v206, 0
	v_mov_b32_e32 v207, 0
	v_mov_b32_e32 v208, 0
	v_mov_b32_e32 v209, 0
	v_mov_b32_e32 v210, 0
	v_mov_b32_e32 v211, 0
	s_add_u32 s10, s20, 0x13aae600
	s_addc_u32 s11, s21, 0
	s_and_saveexec_b64 s[22:23], s[98:99]
	global_load_dwordx4 v[204:207], v192, s[10:11]
	s_add_u32 s100, s20, 0x13a56600
	s_addc_u32 s101, s21, 0
	s_and_b64 exec, exec, s[40:41]
	global_load_dwordx4 v[200:203], v192, s[100:101]
	s_add_u32 s10, s20, 0x13b06600
	s_addc_u32 s11, s21, 0
	s_and_b64 exec, s[22:23], s[98:99]
	s_and_b64 exec, exec, s[42:43]
	global_load_dwordx4 v[208:211], v192, s[10:11]
	s_mov_b64 exec, s[22:23]
	s_waitcnt vmcnt(0)
	s_branch .LBB0_719

; __device__ __forceinline__ unsigned pk_bf16(float a, float b) { f32x2 v = {a, b}; bf2_t r = __builtin_convertvector(v, bf2_t); return __builtin_bit_cast(unsigned, r); }
; __device__ __forceinline__ float bf_lo(unsigned u) { return __uint_as_float(u << 16); }
; __device__ __forceinline__ float bf_hi(unsigned u) { return __uint_as_float(u & 0xffff0000u); }
; __device__ void phase_conv(const Params& p, int l, int nrows) {
;     ...
;         for (int i = 0; i < 16; ++i) {
;             const bf16_t* np = gp + (size_t)(i + 1) * FF;
;             const bool v = (c0 + i + 1) < W;
;             R[0] = (v && up) ? *(const u32x4*)(np - (size_t)64 * FF) : zero; R[1] = v ? *(const u32x4*)np : zero; R[2] = (v && dn) ? *(const u32x4*)(np + (size_t)64 * FF) : zero;
;             float acc[8];
; #pragma unroll
;             for (int j = 0; j < 8; ++j) acc[j] = bias[j];
; #pragma unroll
;             for (int rr = 0; rr < 3; ++rr) {
; #pragma unroll
;                 for (int j = 0; j < 4; ++j) {
;                     acc[2 * j] += bf_lo(L[rr][j]) * tp[rr * 3 + 0][2 * j] + bf_lo(M[rr][j]) * tp[rr * 3 + 1][2 * j] + bf_lo(R[rr][j]) * tp[rr * 3 + 2][2 * j];
;                     acc[2 * j + 1] += bf_hi(L[rr][j]) * tp[rr * 3 + 0][2 * j + 1] + bf_hi(M[rr][j]) * tp[rr * 3 + 1][2 * j + 1] + bf_hi(R[rr][j]) * tp[rr * 3 + 2][2 * j + 1];
;                 }
;             }
;             bf16_t* ap = Aup + (size_t)(tok0 + i) * FF + f0;
;             const u32x4 av = __builtin_nontemporal_load((const u32x4*)ap);
;             u32x4 wv;
; #pragma unroll
;             for (int j = 0; j < 4; ++j) wv[j] = pk_bf16(bf_lo(av[j]) * gelu_f(acc[2 * j]), bf_hi(av[j]) * gelu_f(acc[2 * j + 1]));
;             *(u32x4*)ap = wv;
; #pragma unroll
;             for (int rr = 0; rr < 3; ++rr) { L[rr] = M[rr]; M[rr] = R[rr]; }
.LBB0_718:
	s_or_b64 exec, exec, s[66:67]
	v_add_co_u32_e32 v10, vcc, 0x7fb6000, v124
	v_pk_mul_f32 v[140:141], v[32:33], v[140:141]
	s_nop 0
	v_addc_co_u32_e32 v11, vcc, 0, v125, vcc
	v_pk_mul_f32 v[124:125], v[12:13], v[174:175]
	v_pk_fma_f32 v[140:141], v[40:41], v[150:151], v[140:141]
	v_pk_fma_f32 v[124:125], v[4:5], v[148:149], v[124:125]
	s_waitcnt vmcnt(1)
	v_mov_b64_e32 v[104:105], v[200:201]
	v_mov_b64_e32 v[106:107], v[202:203]
	v_mov_b64_e32 v[100:101], v[204:205]
	v_mov_b64_e32 v[102:103], v[206:207]
	v_mov_b64_e32 v[96:97], v[208:209]
	v_mov_b64_e32 v[98:99], v[210:211]
	v_mov_b64_e32 v[108:109], v[196:197]
	v_mov_b64_e32 v[110:111], v[198:199]
	v_add_u32_e32 v214, 1, v188
	v_cmp_lt_u32_e64 s[98:99], v214, v187
	s_add_u32 s100, s20, 0x7fb8000
	s_addc_u32 s101, s21, 0
	global_load_dwordx4 v[196:199], v192, s[100:101] nt
	v_mov_b32_e32 v200, 0
	v_mov_b32_e32 v201, 0
	v_mov_b32_e32 v202, 0
	v_mov_b32_e32 v203, 0
	v_mov_b32_e32 v204, 0
	v_mov_b32_e32 v205, 0
	v_mov_b32_e32 v206, 0
	v_mov_b32_e32 v207, 0
	v_mov_b32_e32 v208, 0
	v_mov_b32_e32 v209, 0
	v_mov_b32_e32 v210, 0
	v_mov_b32_e32 v211, 0
	s_add_u32 s10, s20, 0x13ab9600
	s_addc_u32 s11, s21, 0
	s_and_saveexec_b64 s[22:23], s[98:99]
	global_load_dwordx4 v[204:207], v192, s[10:11]
	s_add_u32 s100, s20, 0x13a61600
	s_addc_u32 s101, s21, 0
	s_and_b64 exec, exec, s[40:41]
	global_load_dwordx4 v[200:203], v192, s[100:101]
	s_add_u32 s10, s20, 0x13b11600
	s_addc_u32 s11, s21, 0
	s_and_b64 exec, s[22:23], s[98:99]
	s_and_b64 exec, exec, s[42:43]
	global_load_dwordx4 v[208:211], v192, s[10:11]
	s_mov_b64 exec, s[22:23]
	v_lshlrev_b32_e32 v148, 16, v104
	v_and_b32_e32 v149, 0xffff0000, v104
	v_pk_fma_f32 v[124:125], v[20:21], v[148:149], v[124:125]
	v_pk_mul_f32 v[148:149], v[28:29], v[164:165]
	v_lshlrev_b32_e32 v164, 16, v100
	v_pk_fma_f32 v[148:149], v[36:37], v[170:171], v[148:149]
	v_and_b32_e32 v165, 0xffff0000, v100
	v_pk_add_f32 v[124:125], v[80:81], v[124:125]
	v_pk_fma_f32 v[148:149], v[44:45], v[164:165], v[148:149]
	v_pk_mul_f32 v[126:127], v[56:57], v[126:127]
	v_pk_add_f32 v[124:125], v[124:125], v[148:149]
	v_pk_mul_f32 v[148:149], v[52:53], v[162:163]
	v_lshlrev_b32_e32 v162, 16, v96
	v_pk_fma_f32 v[148:149], v[60:61], v[168:169], v[148:149]
	v_and_b32_e32 v163, 0xffff0000, v96
	v_pk_fma_f32 v[148:149], v[68:69], v[162:163], v[148:149]
	v_pk_fma_f32 v[126:127], v[64:65], v[144:145], v[126:127]
	v_pk_add_f32 v[148:149], v[124:125], v[148:149]
	v_mov_b64_e32 v[124:125], s[90:91]
	v_fma_f32 v9, |v148|, s80, 1.0
	v_pk_mul_f32 v[164:165], v[148:149], v[148:149]
	v_rcp_f32_e32 v162, v9
	v_mul_f32_e32 v9, 0xbf38aa3b, v164
	v_exp_f32_e32 v164, v9
	v_fma_f32 v9, |v149|, s80, 1.0
	v_rcp_f32_e32 v163, v9
	v_mul_f32_e32 v9, 0xbf38aa3b, v165
	v_exp_f32_e32 v165, v9
	v_cmp_gt_f32_e32 vcc, 0, v148
	v_pk_fma_f32 v[170:171], v[162:163], s[68:69], v[124:125] op_sel_hi:[1,0,0]
	v_cmp_gt_f32_e64 s[0:1], 0, v149
	v_pk_fma_f32 v[170:171], v[162:163], v[170:171], s[44:45] op_sel_hi:[1,1,0]
	v_pk_mul_f32 v[116:117], v[34:35], v[116:117]
	v_pk_fma_f32 v[170:171], v[162:163], v[170:171], s[84:85] op_sel_hi:[1,1,0]
	v_pk_fma_f32 v[116:117], v[42:43], v[142:143], v[116:117]
	v_pk_fma_f32 v[170:171], v[162:163], v[170:171], s[64:65] op_sel_hi:[1,1,0]
	v_pk_mul_f32 v[114:115], v[58:59], v[114:115]
	v_pk_mul_f32 v[162:163], v[162:163], v[170:171]
	v_pk_fma_f32 v[112:113], v[66:67], v[112:113], v[114:115]
	v_pk_mul_f32 v[162:163], v[164:165], v[162:163]
	v_lshlrev_b32_e32 v114, 16, v99
	v_pk_mul_f32 v[164:165], v[148:149], v[162:163]
	v_pk_fma_f32 v[148:149], v[148:149], v[162:163], v[148:149] neg_lo:[1,0,0] neg_hi:[1,0,0]
	v_and_b32_e32 v115, 0xffff0000, v99
	v_cndmask_b32_e64 v149, v149, v165, s[0:1]
	v_cndmask_b32_e32 v148, v148, v164, vcc
	v_pk_fma_f32 v[112:113], v[74:75], v[114:115], v[112:113]
	s_add_u32 s88, s88, 0xb000
	s_addc_u32 s89, s89, 0
	v_add_u32_e32 v188, 8, v188
	s_cmp_eq_u32 s88, 0x16000
	s_nop 0
	v_lshlrev_b32_e32 v168, 16, v108
	v_and_b32_e32 v169, 0xffff0000, v108
	v_pk_mul_f32 v[148:149], v[148:149], v[168:169]
	v_lshlrev_b32_e32 v144, 16, v110
	v_cvt_pk_bf16_f32 v108, v148, v149
	v_pk_mul_f32 v[148:149], v[14:15], v[172:173]
	v_and_b32_e32 v145, 0xffff0000, v110
	v_pk_fma_f32 v[146:147], v[6:7], v[146:147], v[148:149]
	v_lshlrev_b32_e32 v148, 16, v105
	v_and_b32_e32 v149, 0xffff0000, v105
	v_pk_fma_f32 v[146:147], v[22:23], v[148:149], v[146:147]
	v_pk_mul_f32 v[148:149], v[30:31], v[160:161]
	v_lshlrev_b32_e32 v160, 16, v101
	v_pk_fma_f32 v[148:149], v[38:39], v[166:167], v[148:149]
	v_and_b32_e32 v161, 0xffff0000, v101
	v_pk_add_f32 v[146:147], v[82:83], v[146:147]
	v_pk_fma_f32 v[148:149], v[46:47], v[160:161], v[148:149]
	s_nop 0
	v_pk_add_f32 v[146:147], v[146:147], v[148:149]
	v_pk_mul_f32 v[148:149], v[54:55], v[158:159]
	v_lshlrev_b32_e32 v158, 16, v109
	v_pk_fma_f32 v[148:149], v[62:63], v[156:157], v[148:149]
	v_lshlrev_b32_e32 v156, 16, v97
	v_and_b32_e32 v157, 0xffff0000, v97
	v_pk_fma_f32 v[148:149], v[70:71], v[156:157], v[148:149]
	v_and_b32_e32 v159, 0xffff0000, v109
	v_pk_add_f32 v[146:147], v[146:147], v[148:149]
	s_nop 0
	v_fma_f32 v9, |v146|, s80, 1.0
	v_pk_mul_f32 v[156:157], v[146:147], v[146:147]
	v_rcp_f32_e32 v148, v9
	v_mul_f32_e32 v9, 0xbf38aa3b, v156
	v_exp_f32_e32 v156, v9
	v_fma_f32 v9, |v147|, s80, 1.0
	v_rcp_f32_e32 v149, v9
	v_mul_f32_e32 v9, 0xbf38aa3b, v157
	v_exp_f32_e32 v157, v9
	v_cmp_gt_f32_e32 vcc, 0, v146
	v_pk_fma_f32 v[160:161], v[148:149], s[68:69], v[124:125] op_sel_hi:[1,0,0]
; __device__ __forceinline__ unsigned pk_bf16(float a, float b) { f32x2 v = {a, b}; bf2_t r = __builtin_convertvector(v, bf2_t); return __builtin_bit_cast(unsigned, r); }
; __device__ __forceinline__ float bf_lo(unsigned u) { return __uint_as_float(u << 16); }
; __device__ __forceinline__ float bf_hi(unsigned u) { return __uint_as_float(u & 0xffff0000u); }
; __device__ void phase_conv(const Params& p, int l, int nrows) {
;     ...
;         for (int i = 0; i < 16; ++i) {
;             const bf16_t* np = gp + (size_t)(i + 1) * FF;
;             const bool v = (c0 + i + 1) < W;
;             R[0] = (v && up) ? *(const u32x4*)(np - (size_t)64 * FF) : zero; R[1] = v ? *(const u32x4*)np : zero; R[2] = (v && dn) ? *(const u32x4*)(np + (size_t)64 * FF) : zero;
;             float acc[8];
; #pragma unroll
;             for (int j = 0; j < 8; ++j) acc[j] = bias[j];
; #pragma unroll
;             for (int rr = 0; rr < 3; ++rr) {
; #pragma unroll
;                 for (int j = 0; j < 4; ++j) {
;                     acc[2 * j] += bf_lo(L[rr][j]) * tp[rr * 3 + 0][2 * j] + bf_lo(M[rr][j]) * tp[rr * 3 + 1][2 * j] + bf_lo(R[rr][j]) * tp[rr * 3 + 2][2 * j];
;                     acc[2 * j + 1] += bf_hi(L[rr][j]) * tp[rr * 3 + 0][2 * j + 1] + bf_hi(M[rr][j]) * tp[rr * 3 + 1][2 * j + 1] + bf_hi(R[rr][j]) * tp[rr * 3 + 2][2 * j + 1];
;                 }
;             }
;             bf16_t* ap = Aup + (size_t)(tok0 + i) * FF + f0;
;             const u32x4 av = __builtin_nontemporal_load((const u32x4*)ap);
;             u32x4 wv;
; #pragma unroll
;             for (int j = 0; j < 4; ++j) wv[j] = pk_bf16(bf_lo(av[j]) * gelu_f(acc[2 * j]), bf_hi(av[j]) * gelu_f(acc[2 * j + 1]));
;             *(u32x4*)ap = wv;
; #pragma unroll
;             for (int rr = 0; rr < 3; ++rr) { L[rr] = M[rr]; M[rr] = R[rr]; }
	v_cmp_gt_f32_e64 s[0:1], 0, v147
	v_pk_fma_f32 v[160:161], v[148:149], v[160:161], s[44:45] op_sel_hi:[1,1,0]
	s_nop 0
	v_pk_fma_f32 v[160:161], v[148:149], v[160:161], s[84:85] op_sel_hi:[1,1,0]
	s_nop 0
	v_pk_fma_f32 v[160:161], v[148:149], v[160:161], s[64:65] op_sel_hi:[1,1,0]
	s_nop 0
	v_pk_mul_f32 v[148:149], v[148:149], v[160:161]
	s_nop 0
	v_pk_mul_f32 v[148:149], v[156:157], v[148:149]
	s_nop 0
	v_pk_mul_f32 v[156:157], v[146:147], v[148:149]
	v_pk_fma_f32 v[146:147], v[146:147], v[148:149], v[146:147] neg_lo:[1,0,0] neg_hi:[1,0,0]
	s_nop 0
	v_cndmask_b32_e64 v147, v147, v157, s[0:1]
	v_cndmask_b32_e32 v146, v146, v156, vcc
	v_pk_mul_f32 v[146:147], v[146:147], v[158:159]
	s_nop 0
	v_cvt_pk_bf16_f32 v109, v146, v147
	v_pk_mul_f32 v[146:147], v[16:17], v[154:155]
	s_nop 0
	v_pk_fma_f32 v[128:129], v[0:1], v[128:129], v[146:147]
	v_lshlrev_b32_e32 v146, 16, v106
	v_and_b32_e32 v147, 0xffff0000, v106
	v_pk_fma_f32 v[128:129], v[24:25], v[146:147], v[128:129]
	v_lshlrev_b32_e32 v146, 16, v102
	v_and_b32_e32 v147, 0xffff0000, v102
	v_pk_add_f32 v[128:129], v[76:77], v[128:129]
	v_pk_fma_f32 v[140:141], v[48:49], v[146:147], v[140:141]
	s_nop 0
	v_pk_add_f32 v[128:129], v[128:129], v[140:141]
	v_lshlrev_b32_e32 v140, 16, v98
	v_and_b32_e32 v141, 0xffff0000, v98
	v_pk_fma_f32 v[126:127], v[72:73], v[140:141], v[126:127]
	s_nop 0
	v_pk_add_f32 v[126:127], v[128:129], v[126:127]
	s_nop 0
	v_fma_f32 v9, |v126|, s80, 1.0
	v_pk_mul_f32 v[140:141], v[126:127], v[126:127]
	v_rcp_f32_e32 v128, v9
	v_mul_f32_e32 v9, 0xbf38aa3b, v140
	v_exp_f32_e32 v140, v9
	v_fma_f32 v9, |v127|, s80, 1.0
	v_rcp_f32_e32 v129, v9
	v_mul_f32_e32 v9, 0xbf38aa3b, v141
	v_exp_f32_e32 v141, v9
	v_cmp_gt_f32_e32 vcc, 0, v126
	v_pk_fma_f32 v[146:147], v[128:129], s[68:69], v[124:125] op_sel_hi:[1,0,0]
	v_cmp_gt_f32_e64 s[0:1], 0, v127
	v_pk_fma_f32 v[146:147], v[128:129], v[146:147], s[44:45] op_sel_hi:[1,1,0]
	s_nop 0
	v_pk_fma_f32 v[146:147], v[128:129], v[146:147], s[84:85] op_sel_hi:[1,1,0]
	s_nop 0
	v_pk_fma_f32 v[146:147], v[128:129], v[146:147], s[64:65] op_sel_hi:[1,1,0]
	s_nop 0
	v_pk_mul_f32 v[128:129], v[128:129], v[146:147]
	s_nop 0
	v_pk_mul_f32 v[128:129], v[140:141], v[128:129]
	s_nop 0
	v_pk_mul_f32 v[140:141], v[126:127], v[128:129]
	v_pk_fma_f32 v[126:127], v[126:127], v[128:129], v[126:127] neg_lo:[1,0,0] neg_hi:[1,0,0]
	s_nop 0
	v_cndmask_b32_e64 v127, v127, v141, s[0:1]
	v_cndmask_b32_e32 v126, v126, v140, vcc
	v_pk_mul_f32 v[126:127], v[126:127], v[144:145]
	s_nop 0
	v_cvt_pk_bf16_f32 v110, v126, v127
	v_pk_mul_f32 v[126:127], v[18:19], v[152:153]
	s_nop 0
	v_pk_fma_f32 v[118:119], v[2:3], v[118:119], v[126:127]
	v_lshlrev_b32_e32 v126, 16, v107
	v_and_b32_e32 v127, 0xffff0000, v107
	v_pk_fma_f32 v[118:119], v[26:27], v[126:127], v[118:119]
	v_lshlrev_b32_e32 v126, 16, v103
	v_and_b32_e32 v127, 0xffff0000, v103
	v_pk_add_f32 v[118:119], v[78:79], v[118:119]
	v_pk_fma_f32 v[116:117], v[50:51], v[126:127], v[116:117]
	s_nop 0
	v_pk_add_f32 v[116:117], v[118:119], v[116:117]
	v_lshlrev_b32_e32 v118, 16, v111
	v_pk_add_f32 v[112:113], v[116:117], v[112:113]
	v_and_b32_e32 v119, 0xffff0000, v111
	v_fma_f32 v9, |v112|, s80, 1.0
	v_pk_mul_f32 v[116:117], v[112:113], v[112:113]
	v_rcp_f32_e32 v114, v9
	v_mul_f32_e32 v9, 0xbf38aa3b, v116
	v_exp_f32_e32 v116, v9
	v_fma_f32 v9, |v113|, s80, 1.0
	v_rcp_f32_e32 v115, v9
	v_mul_f32_e32 v9, 0xbf38aa3b, v117
	v_exp_f32_e32 v117, v9
	v_cmp_gt_f32_e32 vcc, 0, v112
	v_pk_fma_f32 v[124:125], v[114:115], s[68:69], v[124:125] op_sel_hi:[1,0,0]
	v_cmp_gt_f32_e64 s[0:1], 0, v113
	v_pk_fma_f32 v[124:125], v[114:115], v[124:125], s[44:45] op_sel_hi:[1,1,0]
	s_nop 0
	v_pk_fma_f32 v[124:125], v[114:115], v[124:125], s[84:85] op_sel_hi:[1,1,0]
	s_nop 0
	v_pk_fma_f32 v[124:125], v[114:115], v[124:125], s[64:65] op_sel_hi:[1,1,0]
	s_nop 0
	v_pk_mul_f32 v[114:115], v[114:115], v[124:125]
	s_nop 0
	v_pk_mul_f32 v[114:115], v[116:117], v[114:115]
	s_nop 0
	v_pk_mul_f32 v[116:117], v[112:113], v[114:115]
	v_pk_fma_f32 v[112:113], v[112:113], v[114:115], v[112:113] neg_lo:[1,0,0] neg_hi:[1,0,0]
	s_nop 0
	v_cndmask_b32_e64 v113, v113, v117, s[0:1]
	v_cndmask_b32_e32 v112, v112, v116, vcc
	v_pk_mul_f32 v[112:113], v[112:113], v[118:119]
	s_nop 0
	v_cvt_pk_bf16_f32 v111, v112, v113
	global_store_dwordx4 v[10:11], v[108:111], off offset:2560
	s_cbranch_scc1 .LBB0_701
.LBB0_719:
	s_add_u32 s20, s62, s88
	s_addc_u32 s21, s63, s89
	v_add_u32_e32 v9, -7, v188
	v_cmp_lt_u32_e64 s[0:1], v9, v187
	v_lshl_add_u64 v[124:125], v[122:123], 0, s[88:89]
	s_and_b64 s[6:7], s[0:1], s[40:41]
	v_mov_b32_e32 v108, 0
	v_mov_b32_e32 v112, 0
	v_mov_b32_e32 v113, 0
	v_mov_b32_e32 v114, 0
	v_mov_b32_e32 v115, 0
	s_and_saveexec_b64 s[66:67], s[6:7]
	s_cbranch_execz .LBB0_721
	v_add_co_u32_e32 v10, vcc, 0x13a56000, v124
	s_nop 1
	v_addc_co_u32_e32 v11, vcc, 0, v125, vcc
.LBB0_721:
	s_or_b64 exec, exec, s[66:67]
	v_mov_b32_e32 v109, 0
	v_mov_b32_e32 v110, 0
	v_mov_b32_e32 v111, 0
	v_mov_b32_e32 v116, 0
	v_mov_b32_e32 v117, 0
	v_mov_b32_e32 v118, 0
	v_mov_b32_e32 v119, 0
	s_and_saveexec_b64 s[66:67], s[0:1]
	s_cbranch_execz .LBB0_725
	v_add_co_u32_e32 v10, vcc, 0x13aae000, v124
	v_mov_b32_e32 v119, 0
	s_nop 0
	v_addc_co_u32_e32 v11, vcc, 0, v125, vcc
	v_mov_b32_e32 v118, 0
	v_mov_b32_e32 v117, 0
	v_mov_b32_e32 v116, 0
	s_and_saveexec_b64 s[0:1], s[42:43]
	s_cbranch_execz .LBB0_724
	v_add_co_u32_e32 v10, vcc, 0x13b06000, v124
	s_nop 1
	v_addc_co_u32_e32 v11, vcc, 0, v125, vcc

; __device__ __forceinline__ unsigned pk_bf16(float a, float b) { f32x2 v = {a, b}; bf2_t r = __builtin_convertvector(v, bf2_t); return __builtin_bit_cast(unsigned, r); }
; __device__ __forceinline__ float bf_lo(unsigned u) { return __uint_as_float(u << 16); }
; __device__ __forceinline__ float bf_hi(unsigned u) { return __uint_as_float(u & 0xffff0000u); }
; __device__ void phase_conv(const Params& p, int l, int nrows) {
;     ...
;         for (int i = 0; i < 16; ++i) {
;             const bf16_t* np = gp + (size_t)(i + 1) * FF;
;             const bool v = (c0 + i + 1) < W;
;             R[0] = (v && up) ? *(const u32x4*)(np - (size_t)64 * FF) : zero; R[1] = v ? *(const u32x4*)np : zero; R[2] = (v && dn) ? *(const u32x4*)(np + (size_t)64 * FF) : zero;
;             float acc[8];
; #pragma unroll
;             for (int j = 0; j < 8; ++j) acc[j] = bias[j];
; #pragma unroll
;             for (int rr = 0; rr < 3; ++rr) {
; #pragma unroll
;                 for (int j = 0; j < 4; ++j) {
;                     acc[2 * j] += bf_lo(L[rr][j]) * tp[rr * 3 + 0][2 * j] + bf_lo(M[rr][j]) * tp[rr * 3 + 1][2 * j] + bf_lo(R[rr][j]) * tp[rr * 3 + 2][2 * j];
;                     acc[2 * j + 1] += bf_hi(L[rr][j]) * tp[rr * 3 + 0][2 * j + 1] + bf_hi(M[rr][j]) * tp[rr * 3 + 1][2 * j + 1] + bf_hi(R[rr][j]) * tp[rr * 3 + 2][2 * j + 1];
;                 }
;             }
;             bf16_t* ap = Aup + (size_t)(tok0 + i) * FF + f0;
;             const u32x4 av = __builtin_nontemporal_load((const u32x4*)ap);
;             u32x4 wv;
; #pragma unroll
;             for (int j = 0; j < 4; ++j) wv[j] = pk_bf16(bf_lo(av[j]) * gelu_f(acc[2 * j]), bf_hi(av[j]) * gelu_f(acc[2 * j + 1]));
;             *(u32x4*)ap = wv;
; #pragma unroll
;             for (int rr = 0; rr < 3; ++rr) { L[rr] = M[rr]; M[rr] = R[rr]; }
.LBB0_725:
	s_or_b64 exec, exec, s[66:67]
	s_mov_b32 s0, 0x7fad000
	v_add_co_u32_e32 v160, vcc, s0, v124
	s_waitcnt vmcnt(1)
	v_lshlrev_b32_e32 v10, 16, v92
	v_addc_co_u32_e32 v161, vcc, 0, v125, vcc
	v_lshlrev_b32_e32 v148, 16, v104
	v_and_b32_e32 v11, 0xffff0000, v92
	v_and_b32_e32 v149, 0xffff0000, v104
	v_lshlrev_b32_e32 v128, 16, v93
	v_lshlrev_b32_e32 v144, 16, v105
	v_and_b32_e32 v129, 0xffff0000, v93
	v_and_b32_e32 v145, 0xffff0000, v105
	v_lshlrev_b32_e32 v104, 16, v94
	v_and_b32_e32 v105, 0xffff0000, v94
	v_lshlrev_b32_e32 v146, 16, v95
	v_and_b32_e32 v147, 0xffff0000, v95
	v_lshlrev_b32_e32 v142, 16, v106
	v_and_b32_e32 v143, 0xffff0000, v106
	v_lshlrev_b32_e32 v140, 16, v107
	v_and_b32_e32 v141, 0xffff0000, v107
	v_pk_mul_f32 v[106:107], v[12:13], v[148:149]
	s_waitcnt vmcnt(1)
	v_mov_b64_e32 v[112:113], v[200:201]
	v_mov_b64_e32 v[114:115], v[202:203]
	v_mov_b64_e32 v[108:109], v[204:205]
	v_mov_b64_e32 v[110:111], v[206:207]
	v_mov_b64_e32 v[116:117], v[208:209]
	v_mov_b64_e32 v[118:119], v[210:211]
	v_mov_b64_e32 v[92:93], v[196:197]
	v_mov_b64_e32 v[94:95], v[198:199]
	v_add_u32_e32 v214, -6, v188
	v_cmp_lt_u32_e64 s[98:99], v214, v187
	s_add_u32 s100, s20, 0x7fae600
	s_addc_u32 s101, s21, 0
	global_load_dwordx4 v[196:199], v192, s[100:101] nt
	v_mov_b32_e32 v200, 0
	v_mov_b32_e32 v201, 0
	v_mov_b32_e32 v202, 0
	v_mov_b32_e32 v203, 0
	v_mov_b32_e32 v204, 0
	v_mov_b32_e32 v205, 0
	v_mov_b32_e32 v206, 0
	v_mov_b32_e32 v207, 0
	v_mov_b32_e32 v208, 0
	v_mov_b32_e32 v209, 0
	v_mov_b32_e32 v210, 0
	v_mov_b32_e32 v211, 0
	s_add_u32 s10, s20, 0x13aafc00
	s_addc_u32 s11, s21, 0
	s_and_saveexec_b64 s[22:23], s[98:99]
	global_load_dwordx4 v[204:207], v192, s[10:11]
	s_add_u32 s100, s20, 0x13a57c00
	s_addc_u32 s101, s21, 0
	s_and_b64 exec, exec, s[40:41]
	global_load_dwordx4 v[200:203], v192, s[100:101]
	s_add_u32 s10, s20, 0x13b07c00
	s_addc_u32 s11, s21, 0
	s_and_b64 exec, s[22:23], s[98:99]
	s_and_b64 exec, exec, s[42:43]
	global_load_dwordx4 v[208:211], v192, s[10:11]
	s_mov_b64 exec, s[22:23]
	v_lshlrev_b32_e32 v150, 16, v100
	v_pk_fma_f32 v[106:107], v[4:5], v[10:11], v[106:107]
	v_lshlrev_b32_e32 v10, 16, v112
	v_and_b32_e32 v11, 0xffff0000, v112
	v_pk_fma_f32 v[106:107], v[20:21], v[10:11], v[106:107]
	v_and_b32_e32 v151, 0xffff0000, v100
	v_pk_add_f32 v[126:127], v[80:81], v[106:107]
	v_lshlrev_b32_e32 v106, 16, v84
	v_and_b32_e32 v107, 0xffff0000, v84
	v_pk_mul_f32 v[106:107], v[28:29], v[106:107]
	v_lshlrev_b32_e32 v154, 16, v96
	v_pk_fma_f32 v[152:153], v[36:37], v[150:151], v[106:107]
	v_lshlrev_b32_e32 v106, 16, v108
	v_and_b32_e32 v107, 0xffff0000, v108
	v_pk_fma_f32 v[152:153], v[44:45], v[106:107], v[152:153]
	v_and_b32_e32 v155, 0xffff0000, v96
	v_pk_add_f32 v[152:153], v[126:127], v[152:153]
	v_lshlrev_b32_e32 v126, 16, v88
	v_and_b32_e32 v127, 0xffff0000, v88
	v_pk_mul_f32 v[126:127], v[52:53], v[126:127]
	v_mov_b64_e32 v[162:163], s[90:91]
	v_pk_fma_f32 v[156:157], v[60:61], v[154:155], v[126:127]
	v_lshlrev_b32_e32 v126, 16, v116
	v_and_b32_e32 v127, 0xffff0000, v116
	v_pk_fma_f32 v[156:157], v[68:69], v[126:127], v[156:157]
	v_lshlrev_b32_e32 v88, 16, v89
	v_pk_add_f32 v[152:153], v[152:153], v[156:157]
	v_and_b32_e32 v89, 0xffff0000, v89
	v_fma_f32 v9, |v152|, s80, 1.0
	v_pk_mul_f32 v[158:159], v[152:153], v[152:153]
	v_rcp_f32_e32 v156, v9
	v_mul_f32_e32 v9, 0xbf38aa3b, v158
	v_exp_f32_e32 v158, v9
	v_fma_f32 v9, |v153|, s80, 1.0
	v_rcp_f32_e32 v157, v9
	v_mul_f32_e32 v9, 0xbf38aa3b, v159
	v_exp_f32_e32 v159, v9
	v_cmp_gt_f32_e32 vcc, 0, v152
	v_pk_fma_f32 v[166:167], v[156:157], s[68:69], v[162:163] op_sel_hi:[1,0,0]
	v_cmp_gt_f32_e64 s[0:1], 0, v153
	v_pk_fma_f32 v[166:167], v[156:157], v[166:167], s[44:45] op_sel_hi:[1,1,0]
	v_lshlrev_b32_e32 v168, 16, v109
	v_pk_fma_f32 v[166:167], v[156:157], v[166:167], s[84:85] op_sel_hi:[1,1,0]
	v_and_b32_e32 v169, 0xffff0000, v109
	v_pk_fma_f32 v[166:167], v[156:157], v[166:167], s[64:65] op_sel_hi:[1,1,0]
	v_pk_mul_f32 v[88:89], v[54:55], v[88:89]
	v_pk_mul_f32 v[156:157], v[156:157], v[166:167]
	v_lshlrev_b32_e32 v174, 16, v97
	v_pk_mul_f32 v[156:157], v[158:159], v[156:157]
	v_and_b32_e32 v175, 0xffff0000, v97
	v_pk_mul_f32 v[158:159], v[152:153], v[156:157]
	v_pk_fma_f32 v[152:153], v[152:153], v[156:157], v[152:153] neg_lo:[1,0,0] neg_hi:[1,0,0]
	v_pk_fma_f32 v[88:89], v[62:63], v[174:175], v[88:89]
	v_cndmask_b32_e64 v153, v153, v159, s[0:1]
	v_cndmask_b32_e32 v152, v152, v158, vcc
	v_lshlrev_b32_e32 v158, 16, v101
	v_and_b32_e32 v159, 0xffff0000, v101
	v_lshlrev_b32_e32 v166, 16, v117
	v_and_b32_e32 v167, 0xffff0000, v117
	v_pk_fma_f32 v[88:89], v[70:71], v[166:167], v[88:89]
	v_lshlrev_b32_e32 v116, 16, v102
	v_and_b32_e32 v117, 0xffff0000, v102
	v_lshlrev_b32_e32 v102, 16, v111
	v_lshlrev_b32_e32 v170, 16, v99
	v_and_b32_e32 v171, 0xffff0000, v99
	s_nop 0
	v_lshlrev_b32_e32 v164, 16, v92
	v_and_b32_e32 v165, 0xffff0000, v92
	v_pk_mul_f32 v[152:153], v[152:153], v[164:165]
	s_nop 0
	v_cvt_pk_bf16_f32 v84, v152, v153
	v_pk_mul_f32 v[152:153], v[14:15], v[144:145]
	s_nop 0
	v_pk_fma_f32 v[152:153], v[6:7], v[128:129], v[152:153]
	v_lshlrev_b32_e32 v128, 16, v113
	v_and_b32_e32 v129, 0xffff0000, v113
	v_pk_fma_f32 v[112:113], v[22:23], v[128:129], v[152:153]
	v_lshlrev_b32_e32 v152, 16, v85
	v_and_b32_e32 v153, 0xffff0000, v85
	v_pk_mul_f32 v[152:153], v[30:31], v[152:153]
	v_pk_add_f32 v[112:113], v[82:83], v[112:113]
	v_pk_fma_f32 v[100:101], v[38:39], v[158:159], v[152:153]
	v_lshlrev_b32_e32 v152, 16, v98
	v_pk_fma_f32 v[100:101], v[46:47], v[168:169], v[100:101]
	v_and_b32_e32 v153, 0xffff0000, v98
	v_pk_add_f32 v[100:101], v[112:113], v[100:101]
; __device__ __forceinline__ unsigned pk_bf16(float a, float b) { f32x2 v = {a, b}; bf2_t r = __builtin_convertvector(v, bf2_t); return __builtin_bit_cast(unsigned, r); }
; __device__ __forceinline__ float bf_lo(unsigned u) { return __uint_as_float(u << 16); }
; __device__ __forceinline__ float bf_hi(unsigned u) { return __uint_as_float(u & 0xffff0000u); }
; __device__ void phase_conv(const Params& p, int l, int nrows) {
;     ...
;         for (int i = 0; i < 16; ++i) {
;             const bf16_t* np = gp + (size_t)(i + 1) * FF;
;             const bool v = (c0 + i + 1) < W;
;             R[0] = (v && up) ? *(const u32x4*)(np - (size_t)64 * FF) : zero; R[1] = v ? *(const u32x4*)np : zero; R[2] = (v && dn) ? *(const u32x4*)(np + (size_t)64 * FF) : zero;
;             float acc[8];
; #pragma unroll
;             for (int j = 0; j < 8; ++j) acc[j] = bias[j];
; #pragma unroll
;             for (int rr = 0; rr < 3; ++rr) {
; #pragma unroll
;                 for (int j = 0; j < 4; ++j) {
;                     acc[2 * j] += bf_lo(L[rr][j]) * tp[rr * 3 + 0][2 * j] + bf_lo(M[rr][j]) * tp[rr * 3 + 1][2 * j] + bf_lo(R[rr][j]) * tp[rr * 3 + 2][2 * j];
;                     acc[2 * j + 1] += bf_hi(L[rr][j]) * tp[rr * 3 + 0][2 * j + 1] + bf_hi(M[rr][j]) * tp[rr * 3 + 1][2 * j + 1] + bf_hi(R[rr][j]) * tp[rr * 3 + 2][2 * j + 1];
;                 }
;             }
;             bf16_t* ap = Aup + (size_t)(tok0 + i) * FF + f0;
;             const u32x4 av = __builtin_nontemporal_load((const u32x4*)ap);
;             u32x4 wv;
; #pragma unroll
;             for (int j = 0; j < 4; ++j) wv[j] = pk_bf16(bf_lo(av[j]) * gelu_f(acc[2 * j]), bf_hi(av[j]) * gelu_f(acc[2 * j + 1]));
;             *(u32x4*)ap = wv;
; #pragma unroll
;             for (int rr = 0; rr < 3; ++rr) { L[rr] = M[rr]; M[rr] = R[rr]; }
	v_lshlrev_b32_e32 v112, 16, v94
	v_pk_add_f32 v[88:89], v[100:101], v[88:89]
	v_lshlrev_b32_e32 v100, 16, v93
	v_fma_f32 v9, |v88|, s80, 1.0
	v_pk_mul_f32 v[96:97], v[88:89], v[88:89]
	v_rcp_f32_e32 v92, v9
	v_mul_f32_e32 v9, 0xbf38aa3b, v96
	v_exp_f32_e32 v96, v9
	v_fma_f32 v9, |v89|, s80, 1.0
	v_and_b32_e32 v101, 0xffff0000, v93
	v_rcp_f32_e32 v93, v9
	v_mul_f32_e32 v9, 0xbf38aa3b, v97
	v_exp_f32_e32 v97, v9
	v_cmp_gt_f32_e32 vcc, 0, v88
	v_pk_fma_f32 v[108:109], v[92:93], s[68:69], v[162:163] op_sel_hi:[1,0,0]
	v_cmp_gt_f32_e64 s[0:1], 0, v89
	v_pk_fma_f32 v[108:109], v[92:93], v[108:109], s[44:45] op_sel_hi:[1,1,0]
	v_and_b32_e32 v113, 0xffff0000, v94
	v_pk_fma_f32 v[108:109], v[92:93], v[108:109], s[84:85] op_sel_hi:[1,1,0]
	v_lshlrev_b32_e32 v94, 16, v95
	v_pk_fma_f32 v[108:109], v[92:93], v[108:109], s[64:65] op_sel_hi:[1,1,0]
	v_and_b32_e32 v95, 0xffff0000, v95
	v_pk_mul_f32 v[92:93], v[92:93], v[108:109]
	v_lshlrev_b32_e32 v108, 16, v118
	v_pk_mul_f32 v[92:93], v[96:97], v[92:93]
	v_and_b32_e32 v109, 0xffff0000, v118
	v_pk_mul_f32 v[96:97], v[88:89], v[92:93]
	v_pk_fma_f32 v[88:89], v[88:89], v[92:93], v[88:89] neg_lo:[1,0,0] neg_hi:[1,0,0]
	v_lshlrev_b32_e32 v92, 16, v86
	v_cndmask_b32_e64 v89, v89, v97, s[0:1]
	v_cndmask_b32_e32 v88, v88, v96, vcc
	v_pk_mul_f32 v[88:89], v[88:89], v[100:101]
	v_and_b32_e32 v93, 0xffff0000, v86
	v_cvt_pk_bf16_f32 v85, v88, v89
	v_pk_mul_f32 v[88:89], v[16:17], v[142:143]
	v_lshlrev_b32_e32 v100, 16, v114
	v_pk_fma_f32 v[88:89], v[0:1], v[104:105], v[88:89]
	v_and_b32_e32 v101, 0xffff0000, v114
	v_pk_mul_f32 v[92:93], v[32:33], v[92:93]
	v_pk_fma_f32 v[88:89], v[24:25], v[100:101], v[88:89]
	v_pk_fma_f32 v[92:93], v[40:41], v[116:117], v[92:93]
	v_lshlrev_b32_e32 v104, 16, v110
	v_and_b32_e32 v105, 0xffff0000, v110
	v_pk_add_f32 v[88:89], v[76:77], v[88:89]
	v_pk_fma_f32 v[92:93], v[48:49], v[104:105], v[92:93]
	s_nop 0
	v_pk_add_f32 v[88:89], v[88:89], v[92:93]
	v_lshlrev_b32_e32 v92, 16, v90
	v_and_b32_e32 v93, 0xffff0000, v90
	v_pk_mul_f32 v[92:93], v[56:57], v[92:93]
	v_lshlrev_b32_e32 v90, 16, v91
	v_pk_fma_f32 v[92:93], v[64:65], v[152:153], v[92:93]
	v_and_b32_e32 v91, 0xffff0000, v91
	v_pk_fma_f32 v[92:93], v[72:73], v[108:109], v[92:93]
	v_pk_mul_f32 v[90:91], v[58:59], v[90:91]
	v_pk_add_f32 v[88:89], v[88:89], v[92:93]
	v_pk_fma_f32 v[90:91], v[66:67], v[170:171], v[90:91]
	v_fma_f32 v9, |v88|, s80, 1.0
	v_pk_mul_f32 v[96:97], v[88:89], v[88:89]
	v_rcp_f32_e32 v92, v9
	v_mul_f32_e32 v9, 0xbf38aa3b, v96
	v_exp_f32_e32 v96, v9
	v_fma_f32 v9, |v89|, s80, 1.0
	v_rcp_f32_e32 v93, v9
	v_mul_f32_e32 v9, 0xbf38aa3b, v97
	v_exp_f32_e32 v97, v9
	v_cmp_gt_f32_e32 vcc, 0, v88
	v_pk_fma_f32 v[156:157], v[92:93], s[68:69], v[162:163] op_sel_hi:[1,0,0]
	v_cmp_gt_f32_e64 s[0:1], 0, v89
	v_pk_fma_f32 v[156:157], v[92:93], v[156:157], s[44:45] op_sel_hi:[1,1,0]
	s_nop 0
	v_pk_fma_f32 v[156:157], v[92:93], v[156:157], s[84:85] op_sel_hi:[1,1,0]
	s_nop 0
	v_pk_fma_f32 v[156:157], v[92:93], v[156:157], s[64:65] op_sel_hi:[1,1,0]
	s_nop 0
	v_pk_mul_f32 v[92:93], v[92:93], v[156:157]
	v_lshlrev_b32_e32 v156, 16, v103
	v_pk_mul_f32 v[92:93], v[96:97], v[92:93]
	v_and_b32_e32 v157, 0xffff0000, v103
	v_pk_mul_f32 v[96:97], v[88:89], v[92:93]
	v_pk_fma_f32 v[88:89], v[88:89], v[92:93], v[88:89] neg_lo:[1,0,0] neg_hi:[1,0,0]
	v_lshlrev_b32_e32 v92, 16, v87
	v_cndmask_b32_e64 v89, v89, v97, s[0:1]
	v_cndmask_b32_e32 v88, v88, v96, vcc
	v_pk_mul_f32 v[88:89], v[88:89], v[112:113]
	v_and_b32_e32 v93, 0xffff0000, v87
	v_cvt_pk_bf16_f32 v86, v88, v89
	v_pk_mul_f32 v[88:89], v[18:19], v[140:141]
	v_lshlrev_b32_e32 v112, 16, v115
	v_pk_fma_f32 v[88:89], v[2:3], v[146:147], v[88:89]
	v_and_b32_e32 v113, 0xffff0000, v115
	v_pk_mul_f32 v[92:93], v[34:35], v[92:93]
	v_pk_fma_f32 v[88:89], v[26:27], v[112:113], v[88:89]
	v_pk_fma_f32 v[92:93], v[42:43], v[156:157], v[92:93]
	v_and_b32_e32 v103, 0xffff0000, v111
	v_pk_add_f32 v[88:89], v[78:79], v[88:89]
	v_pk_fma_f32 v[92:93], v[50:51], v[102:103], v[92:93]
	v_lshlrev_b32_e32 v146, 16, v119
	v_and_b32_e32 v147, 0xffff0000, v119
	v_pk_add_f32 v[88:89], v[88:89], v[92:93]
	v_pk_fma_f32 v[90:91], v[74:75], v[146:147], v[90:91]
	s_nop 0
	v_pk_add_f32 v[88:89], v[88:89], v[90:91]
	s_nop 0
	v_fma_f32 v9, |v88|, s80, 1.0
	v_pk_mul_f32 v[92:93], v[88:89], v[88:89]
	v_rcp_f32_e32 v90, v9
	v_mul_f32_e32 v9, 0xbf38aa3b, v92
	v_exp_f32_e32 v92, v9
	v_fma_f32 v9, |v89|, s80, 1.0
	v_rcp_f32_e32 v91, v9
	v_mul_f32_e32 v9, 0xbf38aa3b, v93
	v_exp_f32_e32 v93, v9
	v_cmp_gt_f32_e32 vcc, 0, v88
	v_pk_fma_f32 v[96:97], v[90:91], s[68:69], v[162:163] op_sel_hi:[1,0,0]
	v_cmp_gt_f32_e64 s[0:1], 0, v89
	v_pk_fma_f32 v[96:97], v[90:91], v[96:97], s[44:45] op_sel_hi:[1,1,0]
	v_add_u32_e32 v9, -6, v188
	v_pk_fma_f32 v[96:97], v[90:91], v[96:97], s[84:85] op_sel_hi:[1,1,0]
	s_nop 0
	v_pk_fma_f32 v[96:97], v[90:91], v[96:97], s[64:65] op_sel_hi:[1,1,0]
	s_nop 0
	v_pk_mul_f32 v[90:91], v[90:91], v[96:97]
	s_nop 0
	v_pk_mul_f32 v[90:91], v[92:93], v[90:91]
	s_nop 0
	v_pk_mul_f32 v[92:93], v[88:89], v[90:91]
	v_pk_fma_f32 v[88:89], v[88:89], v[90:91], v[88:89] neg_lo:[1,0,0] neg_hi:[1,0,0]
	v_mov_b32_e32 v90, 0
	v_cndmask_b32_e64 v89, v89, v93, s[0:1]
	v_cndmask_b32_e32 v88, v88, v92, vcc
	v_pk_mul_f32 v[88:89], v[88:89], v[94:95]
	v_cmp_lt_u32_e64 s[0:1], v9, v187
	v_cvt_pk_bf16_f32 v87, v88, v89
	global_store_dwordx4 v[160:161], v[84:87], off
	s_and_b64 s[6:7], s[0:1], s[40:41]
	v_mov_b32_e32 v88, 0
	v_mov_b32_e32 v84, 0
	v_mov_b32_e32 v89, 0
	v_mov_b32_e32 v91, 0
	s_and_saveexec_b64 s[66:67], s[6:7]
	s_cbranch_execz .LBB0_727
	v_add_co_u32_e32 v86, vcc, 0x13a57000, v124
	s_nop 1
	v_addc_co_u32_e32 v87, vcc, 0, v125, vcc
.LBB0_727:
	s_or_b64 exec, exec, s[66:67]
	v_mov_b32_e32 v85, 0
	v_mov_b32_e32 v86, 0
	v_mov_b32_e32 v87, 0
	v_mov_b32_e32 v92, 0
	v_mov_b32_e32 v93, 0
	v_mov_b32_e32 v94, 0
	v_mov_b32_e32 v95, 0
	s_and_saveexec_b64 s[66:67], s[0:1]
	s_cbranch_execz .LBB0_731
	v_add_co_u32_e32 v84, vcc, 0x13aaf000, v124
	v_mov_b32_e32 v95, 0
	s_nop 0
	v_addc_co_u32_e32 v85, vcc, 0, v125, vcc
	v_mov_b32_e32 v94, 0
	v_mov_b32_e32 v93, 0
	v_mov_b32_e32 v92, 0
	s_and_saveexec_b64 s[0:1], s[42:43]
	s_cbranch_execz .LBB0_730
	v_add_co_u32_e32 v92, vcc, 0x13b07000, v124
	s_nop 1
	v_addc_co_u32_e32 v93, vcc, 0, v125, vcc

; __device__ __forceinline__ unsigned pk_bf16(float a, float b) { f32x2 v = {a, b}; bf2_t r = __builtin_convertvector(v, bf2_t); return __builtin_bit_cast(unsigned, r); }
; __device__ __forceinline__ float bf_lo(unsigned u) { return __uint_as_float(u << 16); }
; __device__ __forceinline__ float bf_hi(unsigned u) { return __uint_as_float(u & 0xffff0000u); }
; __device__ void phase_conv(const Params& p, int l, int nrows) {
;     ...
;         for (int i = 0; i < 16; ++i) {
;             const bf16_t* np = gp + (size_t)(i + 1) * FF;
;             const bool v = (c0 + i + 1) < W;
;             R[0] = (v && up) ? *(const u32x4*)(np - (size_t)64 * FF) : zero; R[1] = v ? *(const u32x4*)np : zero; R[2] = (v && dn) ? *(const u32x4*)(np + (size_t)64 * FF) : zero;
;             float acc[8];
; #pragma unroll
;             for (int j = 0; j < 8; ++j) acc[j] = bias[j];
; #pragma unroll
;             for (int rr = 0; rr < 3; ++rr) {
; #pragma unroll
;                 for (int j = 0; j < 4; ++j) {
;                     acc[2 * j] += bf_lo(L[rr][j]) * tp[rr * 3 + 0][2 * j] + bf_lo(M[rr][j]) * tp[rr * 3 + 1][2 * j] + bf_lo(R[rr][j]) * tp[rr * 3 + 2][2 * j];
;                     acc[2 * j + 1] += bf_hi(L[rr][j]) * tp[rr * 3 + 0][2 * j + 1] + bf_hi(M[rr][j]) * tp[rr * 3 + 1][2 * j + 1] + bf_hi(R[rr][j]) * tp[rr * 3 + 2][2 * j + 1];
;                 }
;             }
;             bf16_t* ap = Aup + (size_t)(tok0 + i) * FF + f0;
;             const u32x4 av = __builtin_nontemporal_load((const u32x4*)ap);
;             u32x4 wv;
; #pragma unroll
;             for (int j = 0; j < 4; ++j) wv[j] = pk_bf16(bf_lo(av[j]) * gelu_f(acc[2 * j]), bf_hi(av[j]) * gelu_f(acc[2 * j + 1]));
;             *(u32x4*)ap = wv;
; #pragma unroll
;             for (int rr = 0; rr < 3; ++rr) { L[rr] = M[rr]; M[rr] = R[rr]; }
.LBB0_731:
	s_or_b64 exec, exec, s[66:67]
	v_add_co_u32_e32 v172, vcc, 0x7fae000, v124
	v_pk_mul_f32 v[110:111], v[12:13], v[10:11]
	s_nop 0
	v_addc_co_u32_e32 v173, vcc, 0, v125, vcc
	v_pk_fma_f32 v[110:111], v[4:5], v[148:149], v[110:111]
	s_waitcnt vmcnt(1)
	v_mov_b64_e32 v[88:89], v[200:201]
	v_mov_b64_e32 v[90:91], v[202:203]
	v_mov_b64_e32 v[84:85], v[204:205]
	v_mov_b64_e32 v[86:87], v[206:207]
	v_mov_b64_e32 v[92:93], v[208:209]
	v_mov_b64_e32 v[94:95], v[210:211]
	v_mov_b64_e32 v[96:97], v[196:197]
	v_mov_b64_e32 v[98:99], v[198:199]
	v_add_u32_e32 v214, -5, v188
	v_cmp_lt_u32_e64 s[98:99], v214, v187
	s_add_u32 s100, s20, 0x7fafc00
	s_addc_u32 s101, s21, 0
	global_load_dwordx4 v[196:199], v192, s[100:101] nt
	v_mov_b32_e32 v200, 0
	v_mov_b32_e32 v201, 0
	v_mov_b32_e32 v202, 0
	v_mov_b32_e32 v203, 0
	v_mov_b32_e32 v204, 0
	v_mov_b32_e32 v205, 0
	v_mov_b32_e32 v206, 0
	v_mov_b32_e32 v207, 0
	v_mov_b32_e32 v208, 0
	v_mov_b32_e32 v209, 0
	v_mov_b32_e32 v210, 0
	v_mov_b32_e32 v211, 0
	s_add_u32 s10, s20, 0x13ab1200
	s_addc_u32 s11, s21, 0
	s_and_saveexec_b64 s[22:23], s[98:99]
	global_load_dwordx4 v[204:207], v192, s[10:11]
	s_add_u32 s100, s20, 0x13a59200
	s_addc_u32 s101, s21, 0
	s_and_b64 exec, exec, s[40:41]
	global_load_dwordx4 v[200:203], v192, s[100:101]
	s_add_u32 s10, s20, 0x13b09200
	s_addc_u32 s11, s21, 0
	s_and_b64 exec, s[22:23], s[98:99]
	s_and_b64 exec, exec, s[42:43]
	global_load_dwordx4 v[208:211], v192, s[10:11]
	s_mov_b64 exec, s[22:23]
	v_lshlrev_b32_e32 v148, 16, v88
	v_and_b32_e32 v149, 0xffff0000, v88
	v_pk_mul_f32 v[114:115], v[28:29], v[150:151]
	v_pk_fma_f32 v[110:111], v[20:21], v[148:149], v[110:111]
	v_pk_fma_f32 v[114:115], v[36:37], v[106:107], v[114:115]
	v_lshlrev_b32_e32 v164, 16, v84
	v_and_b32_e32 v165, 0xffff0000, v84
	v_pk_add_f32 v[110:111], v[80:81], v[110:111]
	v_pk_fma_f32 v[114:115], v[44:45], v[164:165], v[114:115]
	v_lshlrev_b32_e32 v162, 16, v92
	v_pk_add_f32 v[110:111], v[110:111], v[114:115]
	v_pk_mul_f32 v[114:115], v[52:53], v[154:155]
	v_and_b32_e32 v163, 0xffff0000, v92
	v_pk_fma_f32 v[114:115], v[60:61], v[126:127], v[114:115]
	v_mov_b64_e32 v[150:151], s[90:91]
	v_pk_fma_f32 v[114:115], v[68:69], v[162:163], v[114:115]
	s_nop 0
	v_lshlrev_b32_e32 v154, 16, v96
	v_pk_add_f32 v[110:111], v[110:111], v[114:115]
	v_and_b32_e32 v155, 0xffff0000, v96
	v_fma_f32 v9, |v110|, s80, 1.0
	v_pk_mul_f32 v[118:119], v[110:111], v[110:111]
	v_rcp_f32_e32 v114, v9
	v_mul_f32_e32 v9, 0xbf38aa3b, v118
	v_exp_f32_e32 v118, v9
	v_fma_f32 v9, |v111|, s80, 1.0
	v_rcp_f32_e32 v115, v9
	v_mul_f32_e32 v9, 0xbf38aa3b, v119
	v_exp_f32_e32 v119, v9
	v_cmp_gt_f32_e32 vcc, 0, v110
	v_pk_fma_f32 v[160:161], v[114:115], s[68:69], v[150:151] op_sel_hi:[1,0,0]
	v_cmp_gt_f32_e64 s[0:1], 0, v111
	v_pk_fma_f32 v[160:161], v[114:115], v[160:161], s[44:45] op_sel_hi:[1,1,0]
	s_nop 0
	v_pk_fma_f32 v[160:161], v[114:115], v[160:161], s[84:85] op_sel_hi:[1,1,0]
	s_nop 0
	v_pk_fma_f32 v[160:161], v[114:115], v[160:161], s[64:65] op_sel_hi:[1,1,0]
	s_nop 0
	v_pk_mul_f32 v[114:115], v[114:115], v[160:161]
	v_lshlrev_b32_e32 v160, 16, v85
	v_pk_mul_f32 v[114:115], v[118:119], v[114:115]
	v_and_b32_e32 v161, 0xffff0000, v85
	v_pk_mul_f32 v[118:119], v[110:111], v[114:115]
	v_pk_fma_f32 v[110:111], v[110:111], v[114:115], v[110:111] neg_lo:[1,0,0] neg_hi:[1,0,0]
	v_lshlrev_b32_e32 v114, 16, v97
	v_cndmask_b32_e64 v111, v111, v119, s[0:1]
	v_cndmask_b32_e32 v110, v110, v118, vcc
	v_pk_mul_f32 v[110:111], v[110:111], v[154:155]
	v_lshlrev_b32_e32 v154, 16, v89
	v_cvt_pk_bf16_f32 v84, v110, v111
	v_pk_mul_f32 v[110:111], v[14:15], v[128:129]
	v_and_b32_e32 v155, 0xffff0000, v89
	v_pk_fma_f32 v[110:111], v[6:7], v[144:145], v[110:111]
	v_and_b32_e32 v115, 0xffff0000, v97
	v_pk_fma_f32 v[88:89], v[22:23], v[154:155], v[110:111]
	v_pk_mul_f32 v[110:111], v[30:31], v[158:159]
	v_pk_add_f32 v[88:89], v[82:83], v[88:89]
	v_pk_fma_f32 v[110:111], v[38:39], v[168:169], v[110:111]
	v_lshlrev_b32_e32 v158, 16, v93
	v_pk_fma_f32 v[110:111], v[46:47], v[160:161], v[110:111]
	v_and_b32_e32 v159, 0xffff0000, v93
	v_pk_add_f32 v[88:89], v[88:89], v[110:111]
	v_pk_mul_f32 v[110:111], v[54:55], v[174:175]
	v_lshlrev_b32_e32 v144, 16, v86
	v_pk_fma_f32 v[110:111], v[62:63], v[166:167], v[110:111]
	v_and_b32_e32 v145, 0xffff0000, v86
	v_pk_fma_f32 v[92:93], v[70:71], v[158:159], v[110:111]
	s_nop 0
	v_pk_add_f32 v[88:89], v[88:89], v[92:93]
	s_nop 0
	v_fma_f32 v9, |v88|, s80, 1.0
	v_pk_mul_f32 v[110:111], v[88:89], v[88:89]
	v_rcp_f32_e32 v92, v9
	v_mul_f32_e32 v9, 0xbf38aa3b, v110
	v_exp_f32_e32 v96, v9
	v_fma_f32 v9, |v89|, s80, 1.0
	v_rcp_f32_e32 v93, v9
	v_mul_f32_e32 v9, 0xbf38aa3b, v111
	v_exp_f32_e32 v97, v9
	v_cmp_gt_f32_e32 vcc, 0, v88
	v_pk_fma_f32 v[118:119], v[92:93], s[68:69], v[150:151] op_sel_hi:[1,0,0]
	v_cmp_gt_f32_e64 s[0:1], 0, v89
	v_pk_fma_f32 v[118:119], v[92:93], v[118:119], s[44:45] op_sel_hi:[1,1,0]
	v_lshlrev_b32_e32 v110, 16, v98
	v_pk_fma_f32 v[118:119], v[92:93], v[118:119], s[84:85] op_sel_hi:[1,1,0]
	v_and_b32_e32 v111, 0xffff0000, v98
	v_pk_fma_f32 v[118:119], v[92:93], v[118:119], s[64:65] op_sel_hi:[1,1,0]
; __device__ __forceinline__ unsigned pk_bf16(float a, float b) { f32x2 v = {a, b}; bf2_t r = __builtin_convertvector(v, bf2_t); return __builtin_bit_cast(unsigned, r); }
; __device__ __forceinline__ float bf_lo(unsigned u) { return __uint_as_float(u << 16); }
; __device__ __forceinline__ float bf_hi(unsigned u) { return __uint_as_float(u & 0xffff0000u); }
; __device__ void phase_conv(const Params& p, int l, int nrows) {
;     ...
;         for (int i = 0; i < 16; ++i) {
;             const bf16_t* np = gp + (size_t)(i + 1) * FF;
;             const bool v = (c0 + i + 1) < W;
;             R[0] = (v && up) ? *(const u32x4*)(np - (size_t)64 * FF) : zero; R[1] = v ? *(const u32x4*)np : zero; R[2] = (v && dn) ? *(const u32x4*)(np + (size_t)64 * FF) : zero;
;             float acc[8];
; #pragma unroll
;             for (int j = 0; j < 8; ++j) acc[j] = bias[j];
; #pragma unroll
;             for (int rr = 0; rr < 3; ++rr) {
; #pragma unroll
;                 for (int j = 0; j < 4; ++j) {
;                     acc[2 * j] += bf_lo(L[rr][j]) * tp[rr * 3 + 0][2 * j] + bf_lo(M[rr][j]) * tp[rr * 3 + 1][2 * j] + bf_lo(R[rr][j]) * tp[rr * 3 + 2][2 * j];
;                     acc[2 * j + 1] += bf_hi(L[rr][j]) * tp[rr * 3 + 0][2 * j + 1] + bf_hi(M[rr][j]) * tp[rr * 3 + 1][2 * j + 1] + bf_hi(R[rr][j]) * tp[rr * 3 + 2][2 * j + 1];
;                 }
;             }
;             bf16_t* ap = Aup + (size_t)(tok0 + i) * FF + f0;
;             const u32x4 av = __builtin_nontemporal_load((const u32x4*)ap);
;             u32x4 wv;
; #pragma unroll
;             for (int j = 0; j < 4; ++j) wv[j] = pk_bf16(bf_lo(av[j]) * gelu_f(acc[2 * j]), bf_hi(av[j]) * gelu_f(acc[2 * j + 1]));
;             *(u32x4*)ap = wv;
; #pragma unroll
;             for (int rr = 0; rr < 3; ++rr) { L[rr] = M[rr]; M[rr] = R[rr]; }
	s_nop 0
	v_pk_mul_f32 v[92:93], v[92:93], v[118:119]
	v_lshlrev_b32_e32 v118, 16, v94
	v_pk_mul_f32 v[92:93], v[96:97], v[92:93]
	v_and_b32_e32 v119, 0xffff0000, v94
	v_pk_mul_f32 v[96:97], v[88:89], v[92:93]
	v_pk_fma_f32 v[88:89], v[88:89], v[92:93], v[88:89] neg_lo:[1,0,0] neg_hi:[1,0,0]
	v_pk_mul_f32 v[92:93], v[32:33], v[116:117]
	v_cndmask_b32_e64 v89, v89, v97, s[0:1]
	v_cndmask_b32_e32 v88, v88, v96, vcc
	v_pk_mul_f32 v[88:89], v[88:89], v[114:115]
	v_lshlrev_b32_e32 v114, 16, v90
	v_cvt_pk_bf16_f32 v85, v88, v89
	v_pk_mul_f32 v[88:89], v[16:17], v[100:101]
	v_and_b32_e32 v115, 0xffff0000, v90
	v_pk_fma_f32 v[88:89], v[0:1], v[142:143], v[88:89]
	v_pk_fma_f32 v[92:93], v[40:41], v[104:105], v[92:93]
	v_pk_fma_f32 v[88:89], v[24:25], v[114:115], v[88:89]
	v_pk_fma_f32 v[92:93], v[48:49], v[144:145], v[92:93]
	v_pk_add_f32 v[88:89], v[76:77], v[88:89]
	v_lshlrev_b32_e32 v142, 16, v95
	v_pk_add_f32 v[88:89], v[88:89], v[92:93]
	v_pk_mul_f32 v[92:93], v[56:57], v[152:153]
	v_and_b32_e32 v143, 0xffff0000, v95
	v_pk_fma_f32 v[92:93], v[64:65], v[108:109], v[92:93]
	v_lshlrev_b32_e32 v94, 16, v99
	v_pk_fma_f32 v[92:93], v[72:73], v[118:119], v[92:93]
	v_and_b32_e32 v95, 0xffff0000, v99
	v_pk_add_f32 v[88:89], v[88:89], v[92:93]
	s_nop 0
	v_fma_f32 v9, |v88|, s80, 1.0
	v_pk_mul_f32 v[96:97], v[88:89], v[88:89]
	v_rcp_f32_e32 v92, v9
	v_mul_f32_e32 v9, 0xbf38aa3b, v96
	v_exp_f32_e32 v96, v9
	v_fma_f32 v9, |v89|, s80, 1.0
	v_rcp_f32_e32 v93, v9
	v_mul_f32_e32 v9, 0xbf38aa3b, v97
	v_exp_f32_e32 v97, v9
	v_cmp_gt_f32_e32 vcc, 0, v88
	v_pk_fma_f32 v[116:117], v[92:93], s[68:69], v[150:151] op_sel_hi:[1,0,0]
	v_cmp_gt_f32_e64 s[0:1], 0, v89
	v_pk_fma_f32 v[116:117], v[92:93], v[116:117], s[44:45] op_sel_hi:[1,1,0]
	s_nop 0
	v_pk_fma_f32 v[116:117], v[92:93], v[116:117], s[84:85] op_sel_hi:[1,1,0]
	s_nop 0
	v_pk_fma_f32 v[116:117], v[92:93], v[116:117], s[64:65] op_sel_hi:[1,1,0]
	s_nop 0
	v_pk_mul_f32 v[92:93], v[92:93], v[116:117]
	v_lshlrev_b32_e32 v116, 16, v87
	v_pk_mul_f32 v[92:93], v[96:97], v[92:93]
	v_and_b32_e32 v117, 0xffff0000, v87
	v_pk_mul_f32 v[96:97], v[88:89], v[92:93]
	v_pk_fma_f32 v[88:89], v[88:89], v[92:93], v[88:89] neg_lo:[1,0,0] neg_hi:[1,0,0]
	s_nop 0
	v_cndmask_b32_e64 v89, v89, v97, s[0:1]
	v_cndmask_b32_e32 v88, v88, v96, vcc
	v_pk_mul_f32 v[88:89], v[88:89], v[110:111]
	v_lshlrev_b32_e32 v110, 16, v91
	v_cvt_pk_bf16_f32 v86, v88, v89
	v_pk_mul_f32 v[88:89], v[18:19], v[112:113]
	v_and_b32_e32 v111, 0xffff0000, v91
	v_pk_fma_f32 v[88:89], v[2:3], v[140:141], v[88:89]
	v_pk_mul_f32 v[90:91], v[34:35], v[156:157]
	v_pk_fma_f32 v[88:89], v[26:27], v[110:111], v[88:89]
	v_pk_fma_f32 v[90:91], v[42:43], v[102:103], v[90:91]
	v_pk_add_f32 v[88:89], v[78:79], v[88:89]
	v_pk_fma_f32 v[90:91], v[50:51], v[116:117], v[90:91]
	s_nop 0
	v_pk_add_f32 v[88:89], v[88:89], v[90:91]
	v_pk_mul_f32 v[90:91], v[58:59], v[170:171]
	s_nop 0
	v_pk_fma_f32 v[90:91], v[66:67], v[146:147], v[90:91]
	s_nop 0
	v_pk_fma_f32 v[90:91], v[74:75], v[142:143], v[90:91]
	s_nop 0
	v_pk_add_f32 v[88:89], v[88:89], v[90:91]
	s_nop 0
	v_fma_f32 v9, |v88|, s80, 1.0
	v_pk_mul_f32 v[92:93], v[88:89], v[88:89]
	v_rcp_f32_e32 v90, v9
	v_mul_f32_e32 v9, 0xbf38aa3b, v92
	v_exp_f32_e32 v92, v9
	v_fma_f32 v9, |v89|, s80, 1.0
	v_rcp_f32_e32 v91, v9
	v_mul_f32_e32 v9, 0xbf38aa3b, v93
	v_exp_f32_e32 v93, v9
	v_cmp_gt_f32_e32 vcc, 0, v88
	v_pk_fma_f32 v[96:97], v[90:91], s[68:69], v[150:151] op_sel_hi:[1,0,0]
	v_cmp_gt_f32_e64 s[0:1], 0, v89
	v_pk_fma_f32 v[96:97], v[90:91], v[96:97], s[44:45] op_sel_hi:[1,1,0]
	v_add_u32_e32 v9, -5, v188
	v_pk_fma_f32 v[96:97], v[90:91], v[96:97], s[84:85] op_sel_hi:[1,1,0]
	s_nop 0
	v_pk_fma_f32 v[96:97], v[90:91], v[96:97], s[64:65] op_sel_hi:[1,1,0]
	s_nop 0
	v_pk_mul_f32 v[90:91], v[90:91], v[96:97]
	s_nop 0
	v_pk_mul_f32 v[90:91], v[92:93], v[90:91]
	s_nop 0
	v_pk_mul_f32 v[92:93], v[88:89], v[90:91]
	v_pk_fma_f32 v[88:89], v[88:89], v[90:91], v[88:89] neg_lo:[1,0,0] neg_hi:[1,0,0]
	v_mov_b32_e32 v90, 0
	v_cndmask_b32_e64 v89, v89, v93, s[0:1]
	v_cndmask_b32_e32 v88, v88, v92, vcc
	v_pk_mul_f32 v[88:89], v[88:89], v[94:95]
	v_cmp_lt_u32_e64 s[0:1], v9, v187
	v_cvt_pk_bf16_f32 v87, v88, v89
	global_store_dwordx4 v[172:173], v[84:87], off offset:1536
	s_and_b64 s[6:7], s[0:1], s[40:41]
	v_mov_b32_e32 v88, 0
	v_mov_b32_e32 v84, 0
	v_mov_b32_e32 v89, 0
	v_mov_b32_e32 v91, 0
	s_and_saveexec_b64 s[66:67], s[6:7]
	s_cbranch_execz .LBB0_733
	v_add_co_u32_e32 v86, vcc, 0x13a59000, v124
	s_nop 1
	v_addc_co_u32_e32 v87, vcc, 0, v125, vcc
.LBB0_733:
	s_or_b64 exec, exec, s[66:67]
	v_mov_b32_e32 v85, 0
	v_mov_b32_e32 v86, 0
	v_mov_b32_e32 v87, 0
	v_mov_b32_e32 v92, 0
	v_mov_b32_e32 v93, 0
	v_mov_b32_e32 v94, 0
	v_mov_b32_e32 v95, 0
	s_and_saveexec_b64 s[66:67], s[0:1]
	s_cbranch_execz .LBB0_737
	v_add_co_u32_e32 v84, vcc, 0x13ab1000, v124
	v_mov_b32_e32 v95, 0
	s_nop 0
	v_addc_co_u32_e32 v85, vcc, 0, v125, vcc
	v_mov_b32_e32 v94, 0
	v_mov_b32_e32 v93, 0
	v_mov_b32_e32 v92, 0
	s_and_saveexec_b64 s[0:1], s[42:43]
	s_cbranch_execz .LBB0_736
	v_add_co_u32_e32 v92, vcc, 0x13b09000, v124
	s_nop 1
	v_addc_co_u32_e32 v93, vcc, 0, v125, vcc

; __device__ __forceinline__ unsigned pk_bf16(float a, float b) { f32x2 v = {a, b}; bf2_t r = __builtin_convertvector(v, bf2_t); return __builtin_bit_cast(unsigned, r); }
; __device__ __forceinline__ float bf_lo(unsigned u) { return __uint_as_float(u << 16); }
; __device__ __forceinline__ float bf_hi(unsigned u) { return __uint_as_float(u & 0xffff0000u); }
; __device__ void phase_conv(const Params& p, int l, int nrows) {
;     ...
;         for (int i = 0; i < 16; ++i) {
;             const bf16_t* np = gp + (size_t)(i + 1) * FF;
;             const bool v = (c0 + i + 1) < W;
;             R[0] = (v && up) ? *(const u32x4*)(np - (size_t)64 * FF) : zero; R[1] = v ? *(const u32x4*)np : zero; R[2] = (v && dn) ? *(const u32x4*)(np + (size_t)64 * FF) : zero;
;             float acc[8];
; #pragma unroll
;             for (int j = 0; j < 8; ++j) acc[j] = bias[j];
; #pragma unroll
;             for (int rr = 0; rr < 3; ++rr) {
; #pragma unroll
;                 for (int j = 0; j < 4; ++j) {
;                     acc[2 * j] += bf_lo(L[rr][j]) * tp[rr * 3 + 0][2 * j] + bf_lo(M[rr][j]) * tp[rr * 3 + 1][2 * j] + bf_lo(R[rr][j]) * tp[rr * 3 + 2][2 * j];
;                     acc[2 * j + 1] += bf_hi(L[rr][j]) * tp[rr * 3 + 0][2 * j + 1] + bf_hi(M[rr][j]) * tp[rr * 3 + 1][2 * j + 1] + bf_hi(R[rr][j]) * tp[rr * 3 + 2][2 * j + 1];
;                 }
;             }
;             bf16_t* ap = Aup + (size_t)(tok0 + i) * FF + f0;
;             const u32x4 av = __builtin_nontemporal_load((const u32x4*)ap);
;             u32x4 wv;
; #pragma unroll
;             for (int j = 0; j < 4; ++j) wv[j] = pk_bf16(bf_lo(av[j]) * gelu_f(acc[2 * j]), bf_hi(av[j]) * gelu_f(acc[2 * j + 1]));
;             *(u32x4*)ap = wv;
; #pragma unroll
;             for (int rr = 0; rr < 3; ++rr) { L[rr] = M[rr]; M[rr] = R[rr]; }
.LBB0_737:
	s_or_b64 exec, exec, s[66:67]
	v_add_co_u32_e32 v172, vcc, 0x7faf000, v124
	v_pk_mul_f32 v[140:141], v[12:13], v[148:149]
	s_nop 0
	v_addc_co_u32_e32 v173, vcc, 0, v125, vcc
	v_pk_fma_f32 v[10:11], v[4:5], v[10:11], v[140:141]
	s_waitcnt vmcnt(1)
	v_mov_b64_e32 v[88:89], v[200:201]
	v_mov_b64_e32 v[90:91], v[202:203]
	v_mov_b64_e32 v[84:85], v[204:205]
	v_mov_b64_e32 v[86:87], v[206:207]
	v_mov_b64_e32 v[92:93], v[208:209]
	v_mov_b64_e32 v[94:95], v[210:211]
	v_mov_b64_e32 v[96:97], v[196:197]
	v_mov_b64_e32 v[98:99], v[198:199]
	v_add_u32_e32 v214, -4, v188
	v_cmp_lt_u32_e64 s[98:99], v214, v187
	s_add_u32 s100, s20, 0x7fb1200
	s_addc_u32 s101, s21, 0
	global_load_dwordx4 v[196:199], v192, s[100:101] nt
	v_mov_b32_e32 v200, 0
	v_mov_b32_e32 v201, 0
	v_mov_b32_e32 v202, 0
	v_mov_b32_e32 v203, 0
	v_mov_b32_e32 v204, 0
	v_mov_b32_e32 v205, 0
	v_mov_b32_e32 v206, 0
	v_mov_b32_e32 v207, 0
	v_mov_b32_e32 v208, 0
	v_mov_b32_e32 v209, 0
	v_mov_b32_e32 v210, 0
	v_mov_b32_e32 v211, 0
	s_add_u32 s10, s20, 0x13ab2800
	s_addc_u32 s11, s21, 0
	s_and_saveexec_b64 s[22:23], s[98:99]
	global_load_dwordx4 v[204:207], v192, s[10:11]
	s_add_u32 s100, s20, 0x13a5a800
	s_addc_u32 s101, s21, 0
	s_and_b64 exec, exec, s[40:41]
	global_load_dwordx4 v[200:203], v192, s[100:101]
	s_add_u32 s10, s20, 0x13b0a800
	s_addc_u32 s11, s21, 0
	s_and_b64 exec, s[22:23], s[98:99]
	s_and_b64 exec, exec, s[42:43]
	global_load_dwordx4 v[208:211], v192, s[10:11]
	s_mov_b64 exec, s[22:23]
	v_lshlrev_b32_e32 v152, 16, v88
	v_and_b32_e32 v153, 0xffff0000, v88
	v_pk_mul_f32 v[106:107], v[28:29], v[106:107]
	v_pk_fma_f32 v[10:11], v[20:21], v[152:153], v[10:11]
	v_pk_fma_f32 v[106:107], v[36:37], v[164:165], v[106:107]
	v_lshlrev_b32_e32 v156, 16, v84
	v_and_b32_e32 v157, 0xffff0000, v84
	v_pk_add_f32 v[10:11], v[80:81], v[10:11]
	v_pk_fma_f32 v[106:107], v[44:45], v[156:157], v[106:107]
	v_lshlrev_b32_e32 v170, 16, v92
	v_pk_add_f32 v[10:11], v[10:11], v[106:107]
	v_pk_mul_f32 v[106:107], v[52:53], v[126:127]
	v_and_b32_e32 v171, 0xffff0000, v92
	v_pk_fma_f32 v[106:107], v[60:61], v[162:163], v[106:107]
	v_mov_b64_e32 v[126:127], s[90:91]
	v_pk_fma_f32 v[106:107], v[68:69], v[170:171], v[106:107]
	s_nop 0
	v_lshlrev_b32_e32 v150, 16, v96
	v_pk_add_f32 v[10:11], v[10:11], v[106:107]
	v_and_b32_e32 v151, 0xffff0000, v96
	v_fma_f32 v9, |v10|, s80, 1.0
	v_pk_mul_f32 v[140:141], v[10:11], v[10:11]
	v_rcp_f32_e32 v106, v9
	v_mul_f32_e32 v9, 0xbf38aa3b, v140
	v_exp_f32_e32 v140, v9
	v_fma_f32 v9, |v11|, s80, 1.0
	v_rcp_f32_e32 v107, v9
	v_mul_f32_e32 v9, 0xbf38aa3b, v141
	v_exp_f32_e32 v141, v9
	v_cmp_gt_f32_e32 vcc, 0, v10
	v_pk_fma_f32 v[174:175], v[106:107], s[68:69], v[126:127] op_sel_hi:[1,0,0]
	v_cmp_gt_f32_e64 s[0:1], 0, v11
	v_pk_fma_f32 v[174:175], v[106:107], v[174:175], s[44:45] op_sel_hi:[1,1,0]
	v_lshlrev_b32_e32 v96, 16, v97
	v_pk_fma_f32 v[174:175], v[106:107], v[174:175], s[84:85] op_sel_hi:[1,1,0]
	v_and_b32_e32 v97, 0xffff0000, v97
	v_pk_fma_f32 v[174:175], v[106:107], v[174:175], s[64:65] op_sel_hi:[1,1,0]
	s_nop 0
	v_pk_mul_f32 v[106:107], v[106:107], v[174:175]
	s_nop 0
	v_pk_mul_f32 v[106:107], v[140:141], v[106:107]
	s_nop 0
	v_pk_mul_f32 v[140:141], v[10:11], v[106:107]
	v_pk_fma_f32 v[10:11], v[10:11], v[106:107], v[10:11] neg_lo:[1,0,0] neg_hi:[1,0,0]
	s_nop 0
	v_cndmask_b32_e64 v11, v11, v141, s[0:1]
	v_cndmask_b32_e32 v10, v10, v140, vcc
	v_pk_mul_f32 v[10:11], v[10:11], v[150:151]
	v_lshlrev_b32_e32 v150, 16, v89
	v_cvt_pk_bf16_f32 v84, v10, v11
	v_pk_mul_f32 v[10:11], v[14:15], v[154:155]
	v_and_b32_e32 v151, 0xffff0000, v89
	v_pk_fma_f32 v[10:11], v[6:7], v[128:129], v[10:11]
	v_pk_mul_f32 v[88:89], v[30:31], v[168:169]
	v_pk_fma_f32 v[10:11], v[22:23], v[150:151], v[10:11]
	v_pk_fma_f32 v[88:89], v[38:39], v[160:161], v[88:89]
	v_lshlrev_b32_e32 v168, 16, v85
	v_and_b32_e32 v169, 0xffff0000, v85
	v_pk_add_f32 v[10:11], v[82:83], v[10:11]
	v_pk_fma_f32 v[88:89], v[46:47], v[168:169], v[88:89]
	v_lshlrev_b32_e32 v140, 16, v86
	v_pk_add_f32 v[10:11], v[10:11], v[88:89]
	v_pk_mul_f32 v[88:89], v[54:55], v[166:167]
	v_lshlrev_b32_e32 v166, 16, v93
	v_pk_fma_f32 v[88:89], v[62:63], v[158:159], v[88:89]
	v_and_b32_e32 v167, 0xffff0000, v93
	v_pk_fma_f32 v[88:89], v[70:71], v[166:167], v[88:89]
	v_and_b32_e32 v141, 0xffff0000, v86
	v_pk_add_f32 v[10:11], v[10:11], v[88:89]
	v_lshlrev_b32_e32 v128, 16, v94
	v_fma_f32 v9, |v10|, s80, 1.0
	v_pk_mul_f32 v[92:93], v[10:11], v[10:11]
	v_rcp_f32_e32 v88, v9
	v_mul_f32_e32 v9, 0xbf38aa3b, v92
	v_exp_f32_e32 v92, v9
	v_fma_f32 v9, |v11|, s80, 1.0
	v_rcp_f32_e32 v89, v9
	v_mul_f32_e32 v9, 0xbf38aa3b, v93
	v_exp_f32_e32 v93, v9
	v_cmp_gt_f32_e32 vcc, 0, v10
	v_pk_fma_f32 v[106:107], v[88:89], s[68:69], v[126:127] op_sel_hi:[1,0,0]
	v_cmp_gt_f32_e64 s[0:1], 0, v11
	v_pk_fma_f32 v[106:107], v[88:89], v[106:107], s[44:45] op_sel_hi:[1,1,0]
	v_and_b32_e32 v129, 0xffff0000, v94
	v_pk_fma_f32 v[106:107], v[88:89], v[106:107], s[84:85] op_sel_hi:[1,1,0]
	v_lshlrev_b32_e32 v94, 16, v99
	v_pk_fma_f32 v[106:107], v[88:89], v[106:107], s[64:65] op_sel_hi:[1,1,0]
	s_nop 0
; __device__ __forceinline__ unsigned pk_bf16(float a, float b) { f32x2 v = {a, b}; bf2_t r = __builtin_convertvector(v, bf2_t); return __builtin_bit_cast(unsigned, r); }
; __device__ __forceinline__ float bf_lo(unsigned u) { return __uint_as_float(u << 16); }
; __device__ __forceinline__ float bf_hi(unsigned u) { return __uint_as_float(u & 0xffff0000u); }
; __device__ void phase_conv(const Params& p, int l, int nrows) {
;     ...
;         for (int i = 0; i < 16; ++i) {
;             const bf16_t* np = gp + (size_t)(i + 1) * FF;
;             const bool v = (c0 + i + 1) < W;
;             R[0] = (v && up) ? *(const u32x4*)(np - (size_t)64 * FF) : zero; R[1] = v ? *(const u32x4*)np : zero; R[2] = (v && dn) ? *(const u32x4*)(np + (size_t)64 * FF) : zero;
;             float acc[8];
; #pragma unroll
;             for (int j = 0; j < 8; ++j) acc[j] = bias[j];
; #pragma unroll
;             for (int rr = 0; rr < 3; ++rr) {
; #pragma unroll
;                 for (int j = 0; j < 4; ++j) {
;                     acc[2 * j] += bf_lo(L[rr][j]) * tp[rr * 3 + 0][2 * j] + bf_lo(M[rr][j]) * tp[rr * 3 + 1][2 * j] + bf_lo(R[rr][j]) * tp[rr * 3 + 2][2 * j];
;                     acc[2 * j + 1] += bf_hi(L[rr][j]) * tp[rr * 3 + 0][2 * j + 1] + bf_hi(M[rr][j]) * tp[rr * 3 + 1][2 * j + 1] + bf_hi(R[rr][j]) * tp[rr * 3 + 2][2 * j + 1];
;                 }
;             }
;             bf16_t* ap = Aup + (size_t)(tok0 + i) * FF + f0;
;             const u32x4 av = __builtin_nontemporal_load((const u32x4*)ap);
;             u32x4 wv;
; #pragma unroll
;             for (int j = 0; j < 4; ++j) wv[j] = pk_bf16(bf_lo(av[j]) * gelu_f(acc[2 * j]), bf_hi(av[j]) * gelu_f(acc[2 * j + 1]));
;             *(u32x4*)ap = wv;
; #pragma unroll
;             for (int rr = 0; rr < 3; ++rr) { L[rr] = M[rr]; M[rr] = R[rr]; }
	v_pk_mul_f32 v[88:89], v[88:89], v[106:107]
	v_lshlrev_b32_e32 v106, 16, v95
	v_pk_mul_f32 v[88:89], v[92:93], v[88:89]
	v_and_b32_e32 v107, 0xffff0000, v95
	v_pk_mul_f32 v[92:93], v[10:11], v[88:89]
	v_pk_fma_f32 v[10:11], v[10:11], v[88:89], v[10:11] neg_lo:[1,0,0] neg_hi:[1,0,0]
	v_pk_mul_f32 v[88:89], v[32:33], v[104:105]
	v_cndmask_b32_e64 v11, v11, v93, s[0:1]
	v_cndmask_b32_e32 v10, v10, v92, vcc
	v_pk_mul_f32 v[10:11], v[10:11], v[96:97]
	v_pk_fma_f32 v[88:89], v[40:41], v[144:145], v[88:89]
	v_cvt_pk_bf16_f32 v85, v10, v11
	v_pk_mul_f32 v[10:11], v[16:17], v[114:115]
	v_pk_fma_f32 v[88:89], v[48:49], v[140:141], v[88:89]
	v_pk_fma_f32 v[10:11], v[0:1], v[100:101], v[10:11]
	v_lshlrev_b32_e32 v100, 16, v90
	v_and_b32_e32 v101, 0xffff0000, v90
	v_pk_fma_f32 v[10:11], v[24:25], v[100:101], v[10:11]
	v_lshlrev_b32_e32 v96, 16, v98
	v_pk_add_f32 v[10:11], v[76:77], v[10:11]
	v_and_b32_e32 v97, 0xffff0000, v98
	v_pk_add_f32 v[10:11], v[10:11], v[88:89]
	v_pk_mul_f32 v[88:89], v[56:57], v[108:109]
	v_lshlrev_b32_e32 v108, 16, v87
	v_pk_fma_f32 v[88:89], v[64:65], v[118:119], v[88:89]
	v_and_b32_e32 v109, 0xffff0000, v87
	v_pk_fma_f32 v[88:89], v[72:73], v[128:129], v[88:89]
	v_and_b32_e32 v95, 0xffff0000, v99
	v_pk_add_f32 v[10:11], v[10:11], v[88:89]
	s_nop 0
	v_fma_f32 v9, |v10|, s80, 1.0
	v_pk_mul_f32 v[92:93], v[10:11], v[10:11]
	v_rcp_f32_e32 v88, v9
	v_mul_f32_e32 v9, 0xbf38aa3b, v92
	v_exp_f32_e32 v92, v9
	v_fma_f32 v9, |v11|, s80, 1.0
	v_rcp_f32_e32 v89, v9
	v_mul_f32_e32 v9, 0xbf38aa3b, v93
	v_exp_f32_e32 v93, v9
	v_cmp_gt_f32_e32 vcc, 0, v10
	v_pk_fma_f32 v[104:105], v[88:89], s[68:69], v[126:127] op_sel_hi:[1,0,0]
	v_cmp_gt_f32_e64 s[0:1], 0, v11
	v_pk_fma_f32 v[104:105], v[88:89], v[104:105], s[44:45] op_sel_hi:[1,1,0]
	s_nop 0
	v_pk_fma_f32 v[104:105], v[88:89], v[104:105], s[84:85] op_sel_hi:[1,1,0]
	s_nop 0
	v_pk_fma_f32 v[104:105], v[88:89], v[104:105], s[64:65] op_sel_hi:[1,1,0]
	s_nop 0
	v_pk_mul_f32 v[88:89], v[88:89], v[104:105]
	s_nop 0
	v_pk_mul_f32 v[88:89], v[92:93], v[88:89]
	s_nop 0
	v_pk_mul_f32 v[92:93], v[10:11], v[88:89]
	v_pk_fma_f32 v[10:11], v[10:11], v[88:89], v[10:11] neg_lo:[1,0,0] neg_hi:[1,0,0]
	s_nop 0
	v_cndmask_b32_e64 v11, v11, v93, s[0:1]
	v_cndmask_b32_e32 v10, v10, v92, vcc
	v_pk_mul_f32 v[10:11], v[10:11], v[96:97]
	s_nop 0
	v_cvt_pk_bf16_f32 v86, v10, v11
	v_pk_mul_f32 v[10:11], v[18:19], v[110:111]
	s_nop 0
	v_pk_fma_f32 v[88:89], v[2:3], v[112:113], v[10:11]
	v_lshlrev_b32_e32 v10, 16, v91
	v_and_b32_e32 v11, 0xffff0000, v91
	v_pk_mul_f32 v[90:91], v[34:35], v[102:103]
	v_pk_fma_f32 v[88:89], v[26:27], v[10:11], v[88:89]
	v_pk_fma_f32 v[90:91], v[42:43], v[116:117], v[90:91]
	v_pk_add_f32 v[88:89], v[78:79], v[88:89]
	v_pk_fma_f32 v[90:91], v[50:51], v[108:109], v[90:91]
	s_nop 0
	v_pk_add_f32 v[88:89], v[88:89], v[90:91]
	v_pk_mul_f32 v[90:91], v[58:59], v[146:147]
	s_nop 0
	v_pk_fma_f32 v[90:91], v[66:67], v[142:143], v[90:91]
	s_nop 0
	v_pk_fma_f32 v[90:91], v[74:75], v[106:107], v[90:91]
	s_nop 0
	v_pk_add_f32 v[88:89], v[88:89], v[90:91]
	s_nop 0
	v_fma_f32 v9, |v88|, s80, 1.0
	v_pk_mul_f32 v[92:93], v[88:89], v[88:89]
	v_rcp_f32_e32 v90, v9
	v_mul_f32_e32 v9, 0xbf38aa3b, v92
	v_exp_f32_e32 v92, v9
	v_fma_f32 v9, |v89|, s80, 1.0
	v_rcp_f32_e32 v91, v9
	v_mul_f32_e32 v9, 0xbf38aa3b, v93
	v_exp_f32_e32 v93, v9
	v_cmp_gt_f32_e32 vcc, 0, v88
	v_pk_fma_f32 v[96:97], v[90:91], s[68:69], v[126:127] op_sel_hi:[1,0,0]
	v_cmp_gt_f32_e64 s[0:1], 0, v89
	v_pk_fma_f32 v[96:97], v[90:91], v[96:97], s[44:45] op_sel_hi:[1,1,0]
	v_add_u32_e32 v9, -4, v188
	v_pk_fma_f32 v[96:97], v[90:91], v[96:97], s[84:85] op_sel_hi:[1,1,0]
	s_nop 0
	v_pk_fma_f32 v[96:97], v[90:91], v[96:97], s[64:65] op_sel_hi:[1,1,0]
	s_nop 0
	v_pk_mul_f32 v[90:91], v[90:91], v[96:97]
	s_nop 0
	v_pk_mul_f32 v[90:91], v[92:93], v[90:91]
	s_nop 0
	v_pk_mul_f32 v[92:93], v[88:89], v[90:91]
	v_pk_fma_f32 v[88:89], v[88:89], v[90:91], v[88:89] neg_lo:[1,0,0] neg_hi:[1,0,0]
	v_mov_b32_e32 v90, 0
	v_cndmask_b32_e64 v89, v89, v93, s[0:1]
	v_cndmask_b32_e32 v88, v88, v92, vcc
	v_pk_mul_f32 v[88:89], v[88:89], v[94:95]
	v_cmp_lt_u32_e64 s[0:1], v9, v187
	v_cvt_pk_bf16_f32 v87, v88, v89
	global_store_dwordx4 v[172:173], v[84:87], off offset:3072
	s_and_b64 s[6:7], s[0:1], s[40:41]
	v_mov_b32_e32 v88, 0
	v_mov_b32_e32 v84, 0
	v_mov_b32_e32 v89, 0
	v_mov_b32_e32 v91, 0
	s_and_saveexec_b64 s[66:67], s[6:7]
	s_cbranch_execz .LBB0_739
	v_add_co_u32_e32 v86, vcc, 0x13a5a000, v124
	s_nop 1
	v_addc_co_u32_e32 v87, vcc, 0, v125, vcc
.LBB0_739:
	s_or_b64 exec, exec, s[66:67]
	v_mov_b32_e32 v85, 0
	v_mov_b32_e32 v86, 0
	v_mov_b32_e32 v87, 0
	v_mov_b32_e32 v92, 0
	v_mov_b32_e32 v93, 0
	v_mov_b32_e32 v94, 0
	v_mov_b32_e32 v95, 0
	s_and_saveexec_b64 s[66:67], s[0:1]
	s_cbranch_execz .LBB0_743
	v_add_co_u32_e32 v84, vcc, 0x13ab2000, v124
	v_mov_b32_e32 v95, 0
	s_nop 0
	v_addc_co_u32_e32 v85, vcc, 0, v125, vcc
	v_mov_b32_e32 v94, 0
	v_mov_b32_e32 v93, 0
	v_mov_b32_e32 v92, 0
	s_and_saveexec_b64 s[0:1], s[42:43]
	s_cbranch_execz .LBB0_742
	v_add_co_u32_e32 v92, vcc, 0x13b0a000, v124
	s_nop 1
	v_addc_co_u32_e32 v93, vcc, 0, v125, vcc

; __device__ __forceinline__ unsigned pk_bf16(float a, float b) { f32x2 v = {a, b}; bf2_t r = __builtin_convertvector(v, bf2_t); return __builtin_bit_cast(unsigned, r); }
; __device__ __forceinline__ float bf_lo(unsigned u) { return __uint_as_float(u << 16); }
; __device__ __forceinline__ float bf_hi(unsigned u) { return __uint_as_float(u & 0xffff0000u); }
; __device__ void phase_conv(const Params& p, int l, int nrows) {
;     ...
;         for (int i = 0; i < 16; ++i) {
;             const bf16_t* np = gp + (size_t)(i + 1) * FF;
;             const bool v = (c0 + i + 1) < W;
;             R[0] = (v && up) ? *(const u32x4*)(np - (size_t)64 * FF) : zero; R[1] = v ? *(const u32x4*)np : zero; R[2] = (v && dn) ? *(const u32x4*)(np + (size_t)64 * FF) : zero;
;             float acc[8];
; #pragma unroll
;             for (int j = 0; j < 8; ++j) acc[j] = bias[j];
; #pragma unroll
;             for (int rr = 0; rr < 3; ++rr) {
; #pragma unroll
;                 for (int j = 0; j < 4; ++j) {
;                     acc[2 * j] += bf_lo(L[rr][j]) * tp[rr * 3 + 0][2 * j] + bf_lo(M[rr][j]) * tp[rr * 3 + 1][2 * j] + bf_lo(R[rr][j]) * tp[rr * 3 + 2][2 * j];
;                     acc[2 * j + 1] += bf_hi(L[rr][j]) * tp[rr * 3 + 0][2 * j + 1] + bf_hi(M[rr][j]) * tp[rr * 3 + 1][2 * j + 1] + bf_hi(R[rr][j]) * tp[rr * 3 + 2][2 * j + 1];
;                 }
;             }
;             bf16_t* ap = Aup + (size_t)(tok0 + i) * FF + f0;
;             const u32x4 av = __builtin_nontemporal_load((const u32x4*)ap);
;             u32x4 wv;
; #pragma unroll
;             for (int j = 0; j < 4; ++j) wv[j] = pk_bf16(bf_lo(av[j]) * gelu_f(acc[2 * j]), bf_hi(av[j]) * gelu_f(acc[2 * j + 1]));
;             *(u32x4*)ap = wv;
; #pragma unroll
;             for (int rr = 0; rr < 3; ++rr) { L[rr] = M[rr]; M[rr] = R[rr]; }
.LBB0_743:
	s_or_b64 exec, exec, s[66:67]
	v_add_co_u32_e32 v112, vcc, 0x7fb1000, v124
	v_pk_mul_f32 v[102:103], v[12:13], v[152:153]
	s_nop 0
	v_addc_co_u32_e32 v113, vcc, 0, v125, vcc
	v_pk_fma_f32 v[102:103], v[4:5], v[148:149], v[102:103]
	s_waitcnt vmcnt(1)
	v_mov_b64_e32 v[88:89], v[200:201]
	v_mov_b64_e32 v[90:91], v[202:203]
	v_mov_b64_e32 v[84:85], v[204:205]
	v_mov_b64_e32 v[86:87], v[206:207]
	v_mov_b64_e32 v[92:93], v[208:209]
	v_mov_b64_e32 v[94:95], v[210:211]
	v_mov_b64_e32 v[96:97], v[196:197]
	v_mov_b64_e32 v[98:99], v[198:199]
	v_add_u32_e32 v214, -3, v188
	v_cmp_lt_u32_e64 s[98:99], v214, v187
	s_add_u32 s100, s20, 0x7fb2800
	s_addc_u32 s101, s21, 0
	global_load_dwordx4 v[196:199], v192, s[100:101] nt
	v_mov_b32_e32 v200, 0
	v_mov_b32_e32 v201, 0
	v_mov_b32_e32 v202, 0
	v_mov_b32_e32 v203, 0
	v_mov_b32_e32 v204, 0
	v_mov_b32_e32 v205, 0
	v_mov_b32_e32 v206, 0
	v_mov_b32_e32 v207, 0
	v_mov_b32_e32 v208, 0
	v_mov_b32_e32 v209, 0
	v_mov_b32_e32 v210, 0
	v_mov_b32_e32 v211, 0
	s_add_u32 s10, s20, 0x13ab3e00
	s_addc_u32 s11, s21, 0
	s_and_saveexec_b64 s[22:23], s[98:99]
	global_load_dwordx4 v[204:207], v192, s[10:11]
	s_add_u32 s100, s20, 0x13a5be00
	s_addc_u32 s101, s21, 0
	s_and_b64 exec, exec, s[40:41]
	global_load_dwordx4 v[200:203], v192, s[100:101]
	s_add_u32 s10, s20, 0x13b0be00
	s_addc_u32 s11, s21, 0
	s_and_b64 exec, s[22:23], s[98:99]
	s_and_b64 exec, exec, s[42:43]
	global_load_dwordx4 v[208:211], v192, s[10:11]
	s_mov_b64 exec, s[22:23]
	v_lshlrev_b32_e32 v148, 16, v88
	v_and_b32_e32 v149, 0xffff0000, v88
	v_pk_mul_f32 v[104:105], v[28:29], v[164:165]
	v_pk_fma_f32 v[102:103], v[20:21], v[148:149], v[102:103]
	v_pk_fma_f32 v[104:105], v[36:37], v[156:157], v[104:105]
	v_lshlrev_b32_e32 v164, 16, v84
	v_and_b32_e32 v165, 0xffff0000, v84
	v_pk_add_f32 v[102:103], v[80:81], v[102:103]
	v_pk_fma_f32 v[104:105], v[44:45], v[164:165], v[104:105]
	v_mov_b64_e32 v[172:173], s[90:91]
	v_pk_add_f32 v[102:103], v[102:103], v[104:105]
	v_pk_mul_f32 v[104:105], v[52:53], v[162:163]
	v_lshlrev_b32_e32 v162, 16, v92
	v_pk_fma_f32 v[104:105], v[60:61], v[170:171], v[104:105]
	v_and_b32_e32 v163, 0xffff0000, v92
	v_pk_fma_f32 v[104:105], v[68:69], v[162:163], v[104:105]
	s_nop 0
	v_lshlrev_b32_e32 v146, 16, v96
	v_pk_add_f32 v[102:103], v[102:103], v[104:105]
	v_and_b32_e32 v147, 0xffff0000, v96
	v_fma_f32 v9, |v102|, s80, 1.0
	v_pk_mul_f32 v[126:127], v[102:103], v[102:103]
	v_rcp_f32_e32 v104, v9
	v_mul_f32_e32 v9, 0xbf38aa3b, v126
	v_exp_f32_e32 v126, v9
	v_fma_f32 v9, |v103|, s80, 1.0
	v_rcp_f32_e32 v105, v9
	v_mul_f32_e32 v9, 0xbf38aa3b, v127
	v_exp_f32_e32 v127, v9
	v_cmp_gt_f32_e32 vcc, 0, v102
	v_pk_fma_f32 v[174:175], v[104:105], s[68:69], v[172:173] op_sel_hi:[1,0,0]
	v_cmp_gt_f32_e64 s[0:1], 0, v103
	v_pk_fma_f32 v[174:175], v[104:105], v[174:175], s[44:45] op_sel_hi:[1,1,0]
	s_nop 0
	v_pk_fma_f32 v[174:175], v[104:105], v[174:175], s[84:85] op_sel_hi:[1,1,0]
	s_nop 0
	v_pk_fma_f32 v[174:175], v[104:105], v[174:175], s[64:65] op_sel_hi:[1,1,0]
	s_nop 0
	v_pk_mul_f32 v[104:105], v[104:105], v[174:175]
	s_nop 0
	v_pk_mul_f32 v[104:105], v[126:127], v[104:105]
	s_nop 0
	v_pk_mul_f32 v[126:127], v[102:103], v[104:105]
	v_pk_fma_f32 v[102:103], v[102:103], v[104:105], v[102:103] neg_lo:[1,0,0] neg_hi:[1,0,0]
	v_lshlrev_b32_e32 v104, 16, v97
	v_cndmask_b32_e64 v103, v103, v127, s[0:1]
	v_cndmask_b32_e32 v102, v102, v126, vcc
	v_pk_mul_f32 v[102:103], v[102:103], v[146:147]
	v_lshlrev_b32_e32 v146, 16, v89
	v_cvt_pk_bf16_f32 v84, v102, v103
	v_pk_mul_f32 v[102:103], v[14:15], v[150:151]
	v_and_b32_e32 v147, 0xffff0000, v89
	v_pk_fma_f32 v[102:103], v[6:7], v[154:155], v[102:103]
	v_and_b32_e32 v105, 0xffff0000, v97
	v_pk_fma_f32 v[88:89], v[22:23], v[146:147], v[102:103]
	v_pk_mul_f32 v[102:103], v[30:31], v[160:161]
	v_lshlrev_b32_e32 v160, 16, v85
	v_pk_fma_f32 v[102:103], v[38:39], v[168:169], v[102:103]
	v_and_b32_e32 v161, 0xffff0000, v85
	v_pk_add_f32 v[88:89], v[82:83], v[88:89]
	v_pk_fma_f32 v[102:103], v[46:47], v[160:161], v[102:103]
	s_nop 0
	v_pk_add_f32 v[88:89], v[88:89], v[102:103]
	v_pk_mul_f32 v[102:103], v[54:55], v[158:159]
	v_lshlrev_b32_e32 v158, 16, v93
	v_pk_fma_f32 v[102:103], v[62:63], v[166:167], v[102:103]
	v_and_b32_e32 v159, 0xffff0000, v93
	v_pk_fma_f32 v[92:93], v[70:71], v[158:159], v[102:103]
	s_nop 0
	v_pk_add_f32 v[88:89], v[88:89], v[92:93]
	s_nop 0
	v_fma_f32 v9, |v88|, s80, 1.0
	v_pk_mul_f32 v[102:103], v[88:89], v[88:89]
	v_rcp_f32_e32 v92, v9
	v_mul_f32_e32 v9, 0xbf38aa3b, v102
	v_exp_f32_e32 v96, v9
	v_fma_f32 v9, |v89|, s80, 1.0
	v_rcp_f32_e32 v93, v9
	v_mul_f32_e32 v9, 0xbf38aa3b, v103
	v_exp_f32_e32 v97, v9
	v_cmp_gt_f32_e32 vcc, 0, v88
	v_pk_fma_f32 v[126:127], v[92:93], s[68:69], v[172:173] op_sel_hi:[1,0,0]
	v_cmp_gt_f32_e64 s[0:1], 0, v89
	v_pk_fma_f32 v[126:127], v[92:93], v[126:127], s[44:45] op_sel_hi:[1,1,0]
	v_lshlrev_b32_e32 v102, 16, v98
	v_pk_fma_f32 v[126:127], v[92:93], v[126:127], s[84:85] op_sel_hi:[1,1,0]
	v_and_b32_e32 v103, 0xffff0000, v98
	v_pk_fma_f32 v[126:127], v[92:93], v[126:127], s[64:65] op_sel_hi:[1,1,0]
	s_nop 0
	v_pk_mul_f32 v[92:93], v[92:93], v[126:127]
; __device__ __forceinline__ unsigned pk_bf16(float a, float b) { f32x2 v = {a, b}; bf2_t r = __builtin_convertvector(v, bf2_t); return __builtin_bit_cast(unsigned, r); }
; __device__ __forceinline__ float bf_lo(unsigned u) { return __uint_as_float(u << 16); }
; __device__ __forceinline__ float bf_hi(unsigned u) { return __uint_as_float(u & 0xffff0000u); }
; __device__ void phase_conv(const Params& p, int l, int nrows) {
;     ...
;         for (int i = 0; i < 16; ++i) {
;             const bf16_t* np = gp + (size_t)(i + 1) * FF;
;             const bool v = (c0 + i + 1) < W;
;             R[0] = (v && up) ? *(const u32x4*)(np - (size_t)64 * FF) : zero; R[1] = v ? *(const u32x4*)np : zero; R[2] = (v && dn) ? *(const u32x4*)(np + (size_t)64 * FF) : zero;
;             float acc[8];
; #pragma unroll
;             for (int j = 0; j < 8; ++j) acc[j] = bias[j];
; #pragma unroll
;             for (int rr = 0; rr < 3; ++rr) {
; #pragma unroll
;                 for (int j = 0; j < 4; ++j) {
;                     acc[2 * j] += bf_lo(L[rr][j]) * tp[rr * 3 + 0][2 * j] + bf_lo(M[rr][j]) * tp[rr * 3 + 1][2 * j] + bf_lo(R[rr][j]) * tp[rr * 3 + 2][2 * j];
;                     acc[2 * j + 1] += bf_hi(L[rr][j]) * tp[rr * 3 + 0][2 * j + 1] + bf_hi(M[rr][j]) * tp[rr * 3 + 1][2 * j + 1] + bf_hi(R[rr][j]) * tp[rr * 3 + 2][2 * j + 1];
;                 }
;             }
;             bf16_t* ap = Aup + (size_t)(tok0 + i) * FF + f0;
;             const u32x4 av = __builtin_nontemporal_load((const u32x4*)ap);
;             u32x4 wv;
; #pragma unroll
;             for (int j = 0; j < 4; ++j) wv[j] = pk_bf16(bf_lo(av[j]) * gelu_f(acc[2 * j]), bf_hi(av[j]) * gelu_f(acc[2 * j + 1]));
;             *(u32x4*)ap = wv;
; #pragma unroll
;             for (int rr = 0; rr < 3; ++rr) { L[rr] = M[rr]; M[rr] = R[rr]; }
	v_lshlrev_b32_e32 v126, 16, v86
	v_pk_mul_f32 v[92:93], v[96:97], v[92:93]
	v_and_b32_e32 v127, 0xffff0000, v86
	v_pk_mul_f32 v[96:97], v[88:89], v[92:93]
	v_pk_fma_f32 v[88:89], v[88:89], v[92:93], v[88:89] neg_lo:[1,0,0] neg_hi:[1,0,0]
	v_pk_mul_f32 v[92:93], v[32:33], v[144:145]
	v_cndmask_b32_e64 v89, v89, v97, s[0:1]
	v_cndmask_b32_e32 v88, v88, v96, vcc
	v_pk_mul_f32 v[88:89], v[88:89], v[104:105]
	v_lshlrev_b32_e32 v104, 16, v90
	v_cvt_pk_bf16_f32 v85, v88, v89
	v_pk_mul_f32 v[88:89], v[16:17], v[100:101]
	v_and_b32_e32 v105, 0xffff0000, v90
	v_pk_fma_f32 v[88:89], v[0:1], v[114:115], v[88:89]
	v_pk_fma_f32 v[92:93], v[40:41], v[140:141], v[92:93]
	v_pk_fma_f32 v[88:89], v[24:25], v[104:105], v[88:89]
	v_pk_fma_f32 v[92:93], v[48:49], v[126:127], v[92:93]
	v_pk_add_f32 v[88:89], v[76:77], v[88:89]
	s_nop 0
	v_pk_add_f32 v[88:89], v[88:89], v[92:93]
	v_pk_mul_f32 v[92:93], v[56:57], v[118:119]
	v_lshlrev_b32_e32 v118, 16, v94
	v_pk_fma_f32 v[92:93], v[64:65], v[128:129], v[92:93]
	v_and_b32_e32 v119, 0xffff0000, v94
	v_pk_fma_f32 v[92:93], v[72:73], v[118:119], v[92:93]
	v_lshlrev_b32_e32 v94, 16, v99
	v_pk_add_f32 v[88:89], v[88:89], v[92:93]
	s_nop 0
	v_fma_f32 v9, |v88|, s80, 1.0
	v_pk_mul_f32 v[96:97], v[88:89], v[88:89]
	v_rcp_f32_e32 v92, v9
	v_mul_f32_e32 v9, 0xbf38aa3b, v96
	v_exp_f32_e32 v96, v9
	v_fma_f32 v9, |v89|, s80, 1.0
	v_rcp_f32_e32 v93, v9
	v_mul_f32_e32 v9, 0xbf38aa3b, v97
	v_exp_f32_e32 v97, v9
	v_cmp_gt_f32_e32 vcc, 0, v88
	v_pk_fma_f32 v[114:115], v[92:93], s[68:69], v[172:173] op_sel_hi:[1,0,0]
	v_cmp_gt_f32_e64 s[0:1], 0, v89
	v_pk_fma_f32 v[114:115], v[92:93], v[114:115], s[44:45] op_sel_hi:[1,1,0]
	s_nop 0
	v_pk_fma_f32 v[114:115], v[92:93], v[114:115], s[84:85] op_sel_hi:[1,1,0]
	s_nop 0
	v_pk_fma_f32 v[114:115], v[92:93], v[114:115], s[64:65] op_sel_hi:[1,1,0]
	s_nop 0
	v_pk_mul_f32 v[92:93], v[92:93], v[114:115]
	v_lshlrev_b32_e32 v114, 16, v95
	v_pk_mul_f32 v[92:93], v[96:97], v[92:93]
	v_and_b32_e32 v115, 0xffff0000, v95
	v_pk_mul_f32 v[96:97], v[88:89], v[92:93]
	v_pk_fma_f32 v[88:89], v[88:89], v[92:93], v[88:89] neg_lo:[1,0,0] neg_hi:[1,0,0]
	v_and_b32_e32 v95, 0xffff0000, v99
	v_cndmask_b32_e64 v89, v89, v97, s[0:1]
	v_cndmask_b32_e32 v88, v88, v96, vcc
	v_pk_mul_f32 v[88:89], v[88:89], v[102:103]
	v_lshlrev_b32_e32 v102, 16, v91
	v_cvt_pk_bf16_f32 v86, v88, v89
	v_pk_mul_f32 v[88:89], v[18:19], v[10:11]
	v_and_b32_e32 v103, 0xffff0000, v91
	v_pk_fma_f32 v[88:89], v[2:3], v[110:111], v[88:89]
	v_pk_mul_f32 v[90:91], v[34:35], v[116:117]
	v_pk_fma_f32 v[88:89], v[26:27], v[102:103], v[88:89]
	v_pk_fma_f32 v[90:91], v[42:43], v[108:109], v[90:91]
	v_lshlrev_b32_e32 v116, 16, v87
	v_and_b32_e32 v117, 0xffff0000, v87
	v_pk_add_f32 v[88:89], v[78:79], v[88:89]
	v_pk_fma_f32 v[90:91], v[50:51], v[116:117], v[90:91]
	s_nop 0
	v_pk_add_f32 v[88:89], v[88:89], v[90:91]
	v_pk_mul_f32 v[90:91], v[58:59], v[142:143]
	s_nop 0
	v_pk_fma_f32 v[90:91], v[66:67], v[106:107], v[90:91]
	s_nop 0
	v_pk_fma_f32 v[90:91], v[74:75], v[114:115], v[90:91]
	s_nop 0
	v_pk_add_f32 v[88:89], v[88:89], v[90:91]
	s_nop 0
	v_fma_f32 v9, |v88|, s80, 1.0
	v_pk_mul_f32 v[92:93], v[88:89], v[88:89]
	v_rcp_f32_e32 v90, v9
	v_mul_f32_e32 v9, 0xbf38aa3b, v92
	v_exp_f32_e32 v92, v9
	v_fma_f32 v9, |v89|, s80, 1.0
	v_rcp_f32_e32 v91, v9
	v_mul_f32_e32 v9, 0xbf38aa3b, v93
	v_exp_f32_e32 v93, v9
	v_cmp_gt_f32_e32 vcc, 0, v88
	v_pk_fma_f32 v[96:97], v[90:91], s[68:69], v[172:173] op_sel_hi:[1,0,0]
	v_cmp_gt_f32_e64 s[0:1], 0, v89
	v_pk_fma_f32 v[96:97], v[90:91], v[96:97], s[44:45] op_sel_hi:[1,1,0]
	v_add_u32_e32 v9, -3, v188
	v_pk_fma_f32 v[96:97], v[90:91], v[96:97], s[84:85] op_sel_hi:[1,1,0]
	s_nop 0
	v_pk_fma_f32 v[96:97], v[90:91], v[96:97], s[64:65] op_sel_hi:[1,1,0]
	s_nop 0
	v_pk_mul_f32 v[90:91], v[90:91], v[96:97]
	s_nop 0
	v_pk_mul_f32 v[90:91], v[92:93], v[90:91]
	s_nop 0
	v_pk_mul_f32 v[92:93], v[88:89], v[90:91]
	v_pk_fma_f32 v[88:89], v[88:89], v[90:91], v[88:89] neg_lo:[1,0,0] neg_hi:[1,0,0]
	v_mov_b32_e32 v90, 0
	v_cndmask_b32_e64 v89, v89, v93, s[0:1]
	v_cndmask_b32_e32 v88, v88, v92, vcc
	v_pk_mul_f32 v[88:89], v[88:89], v[94:95]
	v_cmp_lt_u32_e64 s[0:1], v9, v187
	v_cvt_pk_bf16_f32 v87, v88, v89
	global_store_dwordx4 v[112:113], v[84:87], off offset:512
	s_and_b64 s[6:7], s[0:1], s[40:41]
	v_mov_b32_e32 v88, 0
	v_mov_b32_e32 v84, 0
	v_mov_b32_e32 v89, 0
	v_mov_b32_e32 v91, 0
	s_and_saveexec_b64 s[66:67], s[6:7]
	s_cbranch_execz .LBB0_745
	v_add_co_u32_e32 v86, vcc, 0x13a5b000, v124
	s_nop 1
	v_addc_co_u32_e32 v87, vcc, 0, v125, vcc
.LBB0_745:
	s_or_b64 exec, exec, s[66:67]
	v_mov_b32_e32 v85, 0
	v_mov_b32_e32 v86, 0
	v_mov_b32_e32 v87, 0
	v_mov_b32_e32 v92, 0
	v_mov_b32_e32 v93, 0
	v_mov_b32_e32 v94, 0
	v_mov_b32_e32 v95, 0
	s_and_saveexec_b64 s[66:67], s[0:1]
	s_cbranch_execz .LBB0_749
	v_add_co_u32_e32 v84, vcc, 0x13ab3000, v124
	v_mov_b32_e32 v95, 0
	s_nop 0
	v_addc_co_u32_e32 v85, vcc, 0, v125, vcc
	v_mov_b32_e32 v94, 0
	v_mov_b32_e32 v93, 0
	v_mov_b32_e32 v92, 0
	s_and_saveexec_b64 s[0:1], s[42:43]
	s_cbranch_execz .LBB0_748
	v_add_co_u32_e32 v92, vcc, 0x13b0b000, v124
	s_nop 1
	v_addc_co_u32_e32 v93, vcc, 0, v125, vcc

; __device__ __forceinline__ unsigned pk_bf16(float a, float b) { f32x2 v = {a, b}; bf2_t r = __builtin_convertvector(v, bf2_t); return __builtin_bit_cast(unsigned, r); }
; __device__ __forceinline__ float bf_lo(unsigned u) { return __uint_as_float(u << 16); }
; __device__ __forceinline__ float bf_hi(unsigned u) { return __uint_as_float(u & 0xffff0000u); }
; __device__ void phase_conv(const Params& p, int l, int nrows) {
;     ...
;         for (int i = 0; i < 16; ++i) {
;             const bf16_t* np = gp + (size_t)(i + 1) * FF;
;             const bool v = (c0 + i + 1) < W;
;             R[0] = (v && up) ? *(const u32x4*)(np - (size_t)64 * FF) : zero; R[1] = v ? *(const u32x4*)np : zero; R[2] = (v && dn) ? *(const u32x4*)(np + (size_t)64 * FF) : zero;
;             float acc[8];
; #pragma unroll
;             for (int j = 0; j < 8; ++j) acc[j] = bias[j];
; #pragma unroll
;             for (int rr = 0; rr < 3; ++rr) {
; #pragma unroll
;                 for (int j = 0; j < 4; ++j) {
;                     acc[2 * j] += bf_lo(L[rr][j]) * tp[rr * 3 + 0][2 * j] + bf_lo(M[rr][j]) * tp[rr * 3 + 1][2 * j] + bf_lo(R[rr][j]) * tp[rr * 3 + 2][2 * j];
;                     acc[2 * j + 1] += bf_hi(L[rr][j]) * tp[rr * 3 + 0][2 * j + 1] + bf_hi(M[rr][j]) * tp[rr * 3 + 1][2 * j + 1] + bf_hi(R[rr][j]) * tp[rr * 3 + 2][2 * j + 1];
;                 }
;             }
;             bf16_t* ap = Aup + (size_t)(tok0 + i) * FF + f0;
;             const u32x4 av = __builtin_nontemporal_load((const u32x4*)ap);
;             u32x4 wv;
; #pragma unroll
;             for (int j = 0; j < 4; ++j) wv[j] = pk_bf16(bf_lo(av[j]) * gelu_f(acc[2 * j]), bf_hi(av[j]) * gelu_f(acc[2 * j + 1]));
;             *(u32x4*)ap = wv;
; #pragma unroll
;             for (int rr = 0; rr < 3; ++rr) { L[rr] = M[rr]; M[rr] = R[rr]; }
.LBB0_749:
	s_or_b64 exec, exec, s[66:67]
	v_add_co_u32_e32 v172, vcc, 0x7fb2000, v124
	v_pk_mul_f32 v[110:111], v[12:13], v[148:149]
	s_nop 0
	v_addc_co_u32_e32 v173, vcc, 0, v125, vcc
	v_pk_fma_f32 v[110:111], v[4:5], v[152:153], v[110:111]
	s_waitcnt vmcnt(1)
	v_mov_b64_e32 v[88:89], v[200:201]
	v_mov_b64_e32 v[90:91], v[202:203]
	v_mov_b64_e32 v[84:85], v[204:205]
	v_mov_b64_e32 v[86:87], v[206:207]
	v_mov_b64_e32 v[92:93], v[208:209]
	v_mov_b64_e32 v[94:95], v[210:211]
	v_mov_b64_e32 v[96:97], v[196:197]
	v_mov_b64_e32 v[98:99], v[198:199]
	v_add_u32_e32 v214, -2, v188
	v_cmp_lt_u32_e64 s[98:99], v214, v187
	s_add_u32 s100, s20, 0x7fb3e00
	s_addc_u32 s101, s21, 0
	global_load_dwordx4 v[196:199], v192, s[100:101] nt
	v_mov_b32_e32 v200, 0
	v_mov_b32_e32 v201, 0
	v_mov_b32_e32 v202, 0
	v_mov_b32_e32 v203, 0
	v_mov_b32_e32 v204, 0
	v_mov_b32_e32 v205, 0
	v_mov_b32_e32 v206, 0
	v_mov_b32_e32 v207, 0
	v_mov_b32_e32 v208, 0
	v_mov_b32_e32 v209, 0
	v_mov_b32_e32 v210, 0
	v_mov_b32_e32 v211, 0
	s_add_u32 s10, s20, 0x13ab5400
	s_addc_u32 s11, s21, 0
	s_and_saveexec_b64 s[22:23], s[98:99]
	global_load_dwordx4 v[204:207], v192, s[10:11]
	s_add_u32 s100, s20, 0x13a5d400
	s_addc_u32 s101, s21, 0
	s_and_b64 exec, exec, s[40:41]
	global_load_dwordx4 v[200:203], v192, s[100:101]
	s_add_u32 s10, s20, 0x13b0d400
	s_addc_u32 s11, s21, 0
	s_and_b64 exec, s[22:23], s[98:99]
	s_and_b64 exec, exec, s[42:43]
	global_load_dwordx4 v[208:211], v192, s[10:11]
	s_mov_b64 exec, s[22:23]
	v_lshlrev_b32_e32 v144, 16, v88
	v_and_b32_e32 v145, 0xffff0000, v88
	v_pk_mul_f32 v[112:113], v[28:29], v[156:157]
	v_pk_fma_f32 v[110:111], v[20:21], v[144:145], v[110:111]
	v_pk_fma_f32 v[112:113], v[36:37], v[164:165], v[112:113]
	v_lshlrev_b32_e32 v156, 16, v84
	v_and_b32_e32 v157, 0xffff0000, v84
	v_pk_add_f32 v[110:111], v[80:81], v[110:111]
	v_pk_fma_f32 v[112:113], v[44:45], v[156:157], v[112:113]
	v_lshlrev_b32_e32 v154, 16, v92
	v_pk_add_f32 v[110:111], v[110:111], v[112:113]
	v_pk_mul_f32 v[112:113], v[52:53], v[170:171]
	v_and_b32_e32 v155, 0xffff0000, v92
	v_pk_fma_f32 v[112:113], v[60:61], v[162:163], v[112:113]
	v_mov_b64_e32 v[170:171], s[90:91]
	v_pk_fma_f32 v[112:113], v[68:69], v[154:155], v[112:113]
	s_nop 0
	v_lshlrev_b32_e32 v152, 16, v96
	v_pk_add_f32 v[110:111], v[110:111], v[112:113]
	v_and_b32_e32 v153, 0xffff0000, v96
	v_fma_f32 v9, |v110|, s80, 1.0
	v_pk_mul_f32 v[142:143], v[110:111], v[110:111]
	v_rcp_f32_e32 v112, v9
	v_mul_f32_e32 v9, 0xbf38aa3b, v142
	v_exp_f32_e32 v142, v9
	v_fma_f32 v9, |v111|, s80, 1.0
	v_rcp_f32_e32 v113, v9
	v_mul_f32_e32 v9, 0xbf38aa3b, v143
	v_exp_f32_e32 v143, v9
	v_cmp_gt_f32_e32 vcc, 0, v110
	v_pk_fma_f32 v[174:175], v[112:113], s[68:69], v[170:171] op_sel_hi:[1,0,0]
	v_cmp_gt_f32_e64 s[0:1], 0, v111
	v_pk_fma_f32 v[174:175], v[112:113], v[174:175], s[44:45] op_sel_hi:[1,1,0]
	s_nop 0
	v_pk_fma_f32 v[174:175], v[112:113], v[174:175], s[84:85] op_sel_hi:[1,1,0]
	s_nop 0
	v_pk_fma_f32 v[174:175], v[112:113], v[174:175], s[64:65] op_sel_hi:[1,1,0]
	s_nop 0
	v_pk_mul_f32 v[112:113], v[112:113], v[174:175]
	s_nop 0
	v_pk_mul_f32 v[112:113], v[142:143], v[112:113]
	s_nop 0
	v_pk_mul_f32 v[142:143], v[110:111], v[112:113]
	v_pk_fma_f32 v[110:111], v[110:111], v[112:113], v[110:111] neg_lo:[1,0,0] neg_hi:[1,0,0]
	v_lshlrev_b32_e32 v112, 16, v97
	v_cndmask_b32_e64 v111, v111, v143, s[0:1]
	v_cndmask_b32_e32 v110, v110, v142, vcc
	v_pk_mul_f32 v[110:111], v[110:111], v[152:153]
	v_lshlrev_b32_e32 v142, 16, v89
	v_cvt_pk_bf16_f32 v84, v110, v111
	v_pk_mul_f32 v[110:111], v[14:15], v[146:147]
	v_and_b32_e32 v143, 0xffff0000, v89
	v_pk_fma_f32 v[110:111], v[6:7], v[150:151], v[110:111]
	v_lshlrev_b32_e32 v152, 16, v85
	v_pk_fma_f32 v[88:89], v[22:23], v[142:143], v[110:111]
	v_pk_mul_f32 v[110:111], v[30:31], v[168:169]
	v_and_b32_e32 v153, 0xffff0000, v85
	v_pk_fma_f32 v[110:111], v[38:39], v[160:161], v[110:111]
	v_pk_add_f32 v[88:89], v[82:83], v[88:89]
	v_pk_fma_f32 v[110:111], v[46:47], v[152:153], v[110:111]
	v_lshlrev_b32_e32 v150, 16, v93
	v_pk_add_f32 v[88:89], v[88:89], v[110:111]
	v_pk_mul_f32 v[110:111], v[54:55], v[166:167]
	v_and_b32_e32 v151, 0xffff0000, v93
	v_pk_fma_f32 v[110:111], v[62:63], v[158:159], v[110:111]
	v_and_b32_e32 v113, 0xffff0000, v97
	v_pk_fma_f32 v[92:93], v[70:71], v[150:151], v[110:111]
	s_nop 0
	v_pk_add_f32 v[88:89], v[88:89], v[92:93]
	s_nop 0
	v_fma_f32 v9, |v88|, s80, 1.0
	v_pk_mul_f32 v[110:111], v[88:89], v[88:89]
	v_rcp_f32_e32 v92, v9
	v_mul_f32_e32 v9, 0xbf38aa3b, v110
	v_exp_f32_e32 v96, v9
	v_fma_f32 v9, |v89|, s80, 1.0
	v_rcp_f32_e32 v93, v9
	v_mul_f32_e32 v9, 0xbf38aa3b, v111
	v_exp_f32_e32 v97, v9
	v_cmp_gt_f32_e32 vcc, 0, v88
	v_pk_fma_f32 v[166:167], v[92:93], s[68:69], v[170:171] op_sel_hi:[1,0,0]
	v_cmp_gt_f32_e64 s[0:1], 0, v89
	v_pk_fma_f32 v[166:167], v[92:93], v[166:167], s[44:45] op_sel_hi:[1,1,0]
	v_lshlrev_b32_e32 v110, 16, v94
	v_pk_fma_f32 v[166:167], v[92:93], v[166:167], s[84:85] op_sel_hi:[1,1,0]
	v_and_b32_e32 v111, 0xffff0000, v94
	v_pk_fma_f32 v[166:167], v[92:93], v[166:167], s[64:65] op_sel_hi:[1,1,0]
	v_lshlrev_b32_e32 v94, 16, v99
	v_pk_mul_f32 v[92:93], v[92:93], v[166:167]
; __device__ __forceinline__ unsigned pk_bf16(float a, float b) { f32x2 v = {a, b}; bf2_t r = __builtin_convertvector(v, bf2_t); return __builtin_bit_cast(unsigned, r); }
; __device__ __forceinline__ float bf_lo(unsigned u) { return __uint_as_float(u << 16); }
; __device__ __forceinline__ float bf_hi(unsigned u) { return __uint_as_float(u & 0xffff0000u); }
; __device__ void phase_conv(const Params& p, int l, int nrows) {
;     ...
;         for (int i = 0; i < 16; ++i) {
;             const bf16_t* np = gp + (size_t)(i + 1) * FF;
;             const bool v = (c0 + i + 1) < W;
;             R[0] = (v && up) ? *(const u32x4*)(np - (size_t)64 * FF) : zero; R[1] = v ? *(const u32x4*)np : zero; R[2] = (v && dn) ? *(const u32x4*)(np + (size_t)64 * FF) : zero;
;             float acc[8];
; #pragma unroll
;             for (int j = 0; j < 8; ++j) acc[j] = bias[j];
; #pragma unroll
;             for (int rr = 0; rr < 3; ++rr) {
; #pragma unroll
;                 for (int j = 0; j < 4; ++j) {
;                     acc[2 * j] += bf_lo(L[rr][j]) * tp[rr * 3 + 0][2 * j] + bf_lo(M[rr][j]) * tp[rr * 3 + 1][2 * j] + bf_lo(R[rr][j]) * tp[rr * 3 + 2][2 * j];
;                     acc[2 * j + 1] += bf_hi(L[rr][j]) * tp[rr * 3 + 0][2 * j + 1] + bf_hi(M[rr][j]) * tp[rr * 3 + 1][2 * j + 1] + bf_hi(R[rr][j]) * tp[rr * 3 + 2][2 * j + 1];
;                 }
;             }
;             bf16_t* ap = Aup + (size_t)(tok0 + i) * FF + f0;
;             const u32x4 av = __builtin_nontemporal_load((const u32x4*)ap);
;             u32x4 wv;
; #pragma unroll
;             for (int j = 0; j < 4; ++j) wv[j] = pk_bf16(bf_lo(av[j]) * gelu_f(acc[2 * j]), bf_hi(av[j]) * gelu_f(acc[2 * j + 1]));
;             *(u32x4*)ap = wv;
; #pragma unroll
;             for (int rr = 0; rr < 3; ++rr) { L[rr] = M[rr]; M[rr] = R[rr]; }
	s_nop 0
	v_pk_mul_f32 v[92:93], v[96:97], v[92:93]
	s_nop 0
	v_pk_mul_f32 v[96:97], v[88:89], v[92:93]
	v_pk_fma_f32 v[88:89], v[88:89], v[92:93], v[88:89] neg_lo:[1,0,0] neg_hi:[1,0,0]
	v_pk_mul_f32 v[92:93], v[32:33], v[140:141]
	v_cndmask_b32_e64 v89, v89, v97, s[0:1]
	v_cndmask_b32_e32 v88, v88, v96, vcc
	v_pk_mul_f32 v[88:89], v[88:89], v[112:113]
	v_pk_fma_f32 v[92:93], v[40:41], v[126:127], v[92:93]
	v_cvt_pk_bf16_f32 v85, v88, v89
	v_pk_mul_f32 v[88:89], v[16:17], v[104:105]
	v_lshlrev_b32_e32 v112, 16, v86
	v_pk_fma_f32 v[88:89], v[0:1], v[100:101], v[88:89]
	v_lshlrev_b32_e32 v100, 16, v90
	v_and_b32_e32 v101, 0xffff0000, v90
	v_pk_fma_f32 v[88:89], v[24:25], v[100:101], v[88:89]
	v_and_b32_e32 v113, 0xffff0000, v86
	v_pk_add_f32 v[88:89], v[76:77], v[88:89]
	v_pk_fma_f32 v[92:93], v[48:49], v[112:113], v[92:93]
	s_nop 0
	v_pk_add_f32 v[88:89], v[88:89], v[92:93]
	v_pk_mul_f32 v[92:93], v[56:57], v[128:129]
	v_lshlrev_b32_e32 v128, 16, v98
	v_pk_fma_f32 v[92:93], v[64:65], v[118:119], v[92:93]
	v_and_b32_e32 v129, 0xffff0000, v98
	v_pk_fma_f32 v[92:93], v[72:73], v[110:111], v[92:93]
	s_nop 0
	v_pk_add_f32 v[88:89], v[88:89], v[92:93]
	s_nop 0
	v_fma_f32 v9, |v88|, s80, 1.0
	v_pk_mul_f32 v[96:97], v[88:89], v[88:89]
	v_rcp_f32_e32 v92, v9
	v_mul_f32_e32 v9, 0xbf38aa3b, v96
	v_exp_f32_e32 v96, v9
	v_fma_f32 v9, |v89|, s80, 1.0
	v_rcp_f32_e32 v93, v9
	v_mul_f32_e32 v9, 0xbf38aa3b, v97
	v_exp_f32_e32 v97, v9
	v_cmp_gt_f32_e32 vcc, 0, v88
	v_pk_fma_f32 v[140:141], v[92:93], s[68:69], v[170:171] op_sel_hi:[1,0,0]
	v_cmp_gt_f32_e64 s[0:1], 0, v89
	v_pk_fma_f32 v[140:141], v[92:93], v[140:141], s[44:45] op_sel_hi:[1,1,0]
	s_nop 0
	v_pk_fma_f32 v[140:141], v[92:93], v[140:141], s[84:85] op_sel_hi:[1,1,0]
	s_nop 0
	v_pk_fma_f32 v[140:141], v[92:93], v[140:141], s[64:65] op_sel_hi:[1,1,0]
	s_nop 0
	v_pk_mul_f32 v[92:93], v[92:93], v[140:141]
	s_nop 0
	v_pk_mul_f32 v[92:93], v[96:97], v[92:93]
	s_nop 0
	v_pk_mul_f32 v[96:97], v[88:89], v[92:93]
	v_pk_fma_f32 v[88:89], v[88:89], v[92:93], v[88:89] neg_lo:[1,0,0] neg_hi:[1,0,0]
	s_nop 0
	v_cndmask_b32_e64 v89, v89, v97, s[0:1]
	v_cndmask_b32_e32 v88, v88, v96, vcc
	v_pk_mul_f32 v[88:89], v[88:89], v[128:129]
	s_nop 0
	v_cvt_pk_bf16_f32 v86, v88, v89
	v_pk_mul_f32 v[88:89], v[18:19], v[102:103]
	s_nop 0
	v_pk_fma_f32 v[88:89], v[2:3], v[10:11], v[88:89]
	v_lshlrev_b32_e32 v10, 16, v91
	v_and_b32_e32 v11, 0xffff0000, v91
	v_pk_mul_f32 v[90:91], v[34:35], v[108:109]
	v_pk_fma_f32 v[88:89], v[26:27], v[10:11], v[88:89]
	v_pk_fma_f32 v[90:91], v[42:43], v[116:117], v[90:91]
	v_lshlrev_b32_e32 v108, 16, v87
	v_and_b32_e32 v109, 0xffff0000, v87
	v_pk_add_f32 v[88:89], v[78:79], v[88:89]
	v_pk_fma_f32 v[90:91], v[50:51], v[108:109], v[90:91]
	s_nop 0
	v_pk_add_f32 v[88:89], v[88:89], v[90:91]
	v_pk_mul_f32 v[90:91], v[58:59], v[106:107]
	v_lshlrev_b32_e32 v106, 16, v95
	v_pk_fma_f32 v[90:91], v[66:67], v[114:115], v[90:91]
	v_and_b32_e32 v107, 0xffff0000, v95
	v_pk_fma_f32 v[90:91], v[74:75], v[106:107], v[90:91]
	v_and_b32_e32 v95, 0xffff0000, v99
	v_pk_add_f32 v[88:89], v[88:89], v[90:91]
	s_nop 0
	v_fma_f32 v9, |v88|, s80, 1.0
	v_pk_mul_f32 v[92:93], v[88:89], v[88:89]
	v_rcp_f32_e32 v90, v9
	v_mul_f32_e32 v9, 0xbf38aa3b, v92
	v_exp_f32_e32 v92, v9
	v_fma_f32 v9, |v89|, s80, 1.0
	v_rcp_f32_e32 v91, v9
	v_mul_f32_e32 v9, 0xbf38aa3b, v93
	v_exp_f32_e32 v93, v9
	v_cmp_gt_f32_e32 vcc, 0, v88
	v_pk_fma_f32 v[96:97], v[90:91], s[68:69], v[170:171] op_sel_hi:[1,0,0]
	v_cmp_gt_f32_e64 s[0:1], 0, v89
	v_pk_fma_f32 v[96:97], v[90:91], v[96:97], s[44:45] op_sel_hi:[1,1,0]
	v_add_u32_e32 v9, -2, v188
	v_pk_fma_f32 v[96:97], v[90:91], v[96:97], s[84:85] op_sel_hi:[1,1,0]
	s_nop 0
	v_pk_fma_f32 v[96:97], v[90:91], v[96:97], s[64:65] op_sel_hi:[1,1,0]
	s_nop 0
	v_pk_mul_f32 v[90:91], v[90:91], v[96:97]
	s_nop 0
	v_pk_mul_f32 v[90:91], v[92:93], v[90:91]
	s_nop 0
	v_pk_mul_f32 v[92:93], v[88:89], v[90:91]
	v_pk_fma_f32 v[88:89], v[88:89], v[90:91], v[88:89] neg_lo:[1,0,0] neg_hi:[1,0,0]
	v_mov_b32_e32 v90, 0
	v_cndmask_b32_e64 v89, v89, v93, s[0:1]
	v_cndmask_b32_e32 v88, v88, v92, vcc
	v_pk_mul_f32 v[88:89], v[88:89], v[94:95]
	v_cmp_lt_u32_e64 s[0:1], v9, v187
	v_cvt_pk_bf16_f32 v87, v88, v89
	global_store_dwordx4 v[172:173], v[84:87], off offset:2048
	s_and_b64 s[6:7], s[0:1], s[40:41]
	v_mov_b32_e32 v88, 0
	v_mov_b32_e32 v84, 0
	v_mov_b32_e32 v89, 0
	v_mov_b32_e32 v91, 0
	s_and_saveexec_b64 s[66:67], s[6:7]
	s_cbranch_execz .LBB0_751
	v_add_co_u32_e32 v86, vcc, 0x13a5d000, v124
	s_nop 1
	v_addc_co_u32_e32 v87, vcc, 0, v125, vcc
.LBB0_751:
	s_or_b64 exec, exec, s[66:67]
	v_mov_b32_e32 v85, 0
	v_mov_b32_e32 v86, 0
	v_mov_b32_e32 v87, 0
	v_mov_b32_e32 v92, 0
	v_mov_b32_e32 v93, 0
	v_mov_b32_e32 v94, 0
	v_mov_b32_e32 v95, 0
	s_and_saveexec_b64 s[66:67], s[0:1]
	s_cbranch_execz .LBB0_755
	v_add_co_u32_e32 v84, vcc, 0x13ab5000, v124
	v_mov_b32_e32 v95, 0
	s_nop 0
	v_addc_co_u32_e32 v85, vcc, 0, v125, vcc
	v_mov_b32_e32 v94, 0
	v_mov_b32_e32 v93, 0
	v_mov_b32_e32 v92, 0
	s_and_saveexec_b64 s[0:1], s[42:43]
	s_cbranch_execz .LBB0_754
	v_add_co_u32_e32 v92, vcc, 0x13b0d000, v124
	s_nop 1
	v_addc_co_u32_e32 v93, vcc, 0, v125, vcc

; __device__ __forceinline__ unsigned pk_bf16(float a, float b) { f32x2 v = {a, b}; bf2_t r = __builtin_convertvector(v, bf2_t); return __builtin_bit_cast(unsigned, r); }
; __device__ __forceinline__ float bf_lo(unsigned u) { return __uint_as_float(u << 16); }
; __device__ __forceinline__ float bf_hi(unsigned u) { return __uint_as_float(u & 0xffff0000u); }
; __device__ void phase_conv(const Params& p, int l, int nrows) {
;     ...
;         for (int i = 0; i < 16; ++i) {
;             const bf16_t* np = gp + (size_t)(i + 1) * FF;
;             const bool v = (c0 + i + 1) < W;
;             R[0] = (v && up) ? *(const u32x4*)(np - (size_t)64 * FF) : zero; R[1] = v ? *(const u32x4*)np : zero; R[2] = (v && dn) ? *(const u32x4*)(np + (size_t)64 * FF) : zero;
;             float acc[8];
; #pragma unroll
;             for (int j = 0; j < 8; ++j) acc[j] = bias[j];
; #pragma unroll
;             for (int rr = 0; rr < 3; ++rr) {
; #pragma unroll
;                 for (int j = 0; j < 4; ++j) {
;                     acc[2 * j] += bf_lo(L[rr][j]) * tp[rr * 3 + 0][2 * j] + bf_lo(M[rr][j]) * tp[rr * 3 + 1][2 * j] + bf_lo(R[rr][j]) * tp[rr * 3 + 2][2 * j];
;                     acc[2 * j + 1] += bf_hi(L[rr][j]) * tp[rr * 3 + 0][2 * j + 1] + bf_hi(M[rr][j]) * tp[rr * 3 + 1][2 * j + 1] + bf_hi(R[rr][j]) * tp[rr * 3 + 2][2 * j + 1];
;                 }
;             }
;             bf16_t* ap = Aup + (size_t)(tok0 + i) * FF + f0;
;             const u32x4 av = __builtin_nontemporal_load((const u32x4*)ap);
;             u32x4 wv;
; #pragma unroll
;             for (int j = 0; j < 4; ++j) wv[j] = pk_bf16(bf_lo(av[j]) * gelu_f(acc[2 * j]), bf_hi(av[j]) * gelu_f(acc[2 * j + 1]));
;             *(u32x4*)ap = wv;
; #pragma unroll
;             for (int rr = 0; rr < 3; ++rr) { L[rr] = M[rr]; M[rr] = R[rr]; }
.LBB0_755:
	s_or_b64 exec, exec, s[66:67]
	v_add_co_u32_e32 v166, vcc, 0x7fb3000, v124
	v_pk_mul_f32 v[128:129], v[12:13], v[144:145]
	s_nop 0
	v_addc_co_u32_e32 v167, vcc, 0, v125, vcc
	v_pk_fma_f32 v[128:129], v[4:5], v[148:149], v[128:129]
	s_waitcnt vmcnt(1)
	v_mov_b64_e32 v[88:89], v[200:201]
	v_mov_b64_e32 v[90:91], v[202:203]
	v_mov_b64_e32 v[84:85], v[204:205]
	v_mov_b64_e32 v[86:87], v[206:207]
	v_mov_b64_e32 v[92:93], v[208:209]
	v_mov_b64_e32 v[94:95], v[210:211]
	v_mov_b64_e32 v[96:97], v[196:197]
	v_mov_b64_e32 v[98:99], v[198:199]
	v_add_u32_e32 v214, -1, v188
	v_cmp_lt_u32_e64 s[98:99], v214, v187
	s_add_u32 s100, s20, 0x7fb5400
	s_addc_u32 s101, s21, 0
	global_load_dwordx4 v[196:199], v192, s[100:101] nt
	v_mov_b32_e32 v200, 0
	v_mov_b32_e32 v201, 0
	v_mov_b32_e32 v202, 0
	v_mov_b32_e32 v203, 0
	v_mov_b32_e32 v204, 0
	v_mov_b32_e32 v205, 0
	v_mov_b32_e32 v206, 0
	v_mov_b32_e32 v207, 0
	v_mov_b32_e32 v208, 0
	v_mov_b32_e32 v209, 0
	v_mov_b32_e32 v210, 0
	v_mov_b32_e32 v211, 0
	s_add_u32 s10, s20, 0x13ab6a00
	s_addc_u32 s11, s21, 0
	s_and_saveexec_b64 s[22:23], s[98:99]
	global_load_dwordx4 v[204:207], v192, s[10:11]
	s_add_u32 s100, s20, 0x13a5ea00
	s_addc_u32 s101, s21, 0
	s_and_b64 exec, exec, s[40:41]
	global_load_dwordx4 v[200:203], v192, s[100:101]
	s_add_u32 s10, s20, 0x13b0ea00
	s_addc_u32 s11, s21, 0
	s_and_b64 exec, s[22:23], s[98:99]
	s_and_b64 exec, exec, s[42:43]
	global_load_dwordx4 v[208:211], v192, s[10:11]
	s_mov_b64 exec, s[22:23]
	v_lshlrev_b32_e32 v148, 16, v88
	v_and_b32_e32 v149, 0xffff0000, v88
	v_pk_mul_f32 v[140:141], v[28:29], v[164:165]
	v_pk_fma_f32 v[128:129], v[20:21], v[148:149], v[128:129]
	v_pk_fma_f32 v[140:141], v[36:37], v[156:157], v[140:141]
	v_lshlrev_b32_e32 v164, 16, v84
	v_and_b32_e32 v165, 0xffff0000, v84
	v_pk_add_f32 v[128:129], v[80:81], v[128:129]
	v_pk_fma_f32 v[140:141], v[44:45], v[164:165], v[140:141]
	v_mov_b64_e32 v[168:169], s[90:91]
	v_pk_add_f32 v[128:129], v[128:129], v[140:141]
	v_pk_mul_f32 v[140:141], v[52:53], v[162:163]
	v_lshlrev_b32_e32 v162, 16, v92
	v_pk_fma_f32 v[140:141], v[60:61], v[154:155], v[140:141]
	v_and_b32_e32 v163, 0xffff0000, v92
	v_pk_fma_f32 v[140:141], v[68:69], v[162:163], v[140:141]
	s_nop 0
	v_lshlrev_b32_e32 v172, 16, v96
	v_pk_add_f32 v[128:129], v[128:129], v[140:141]
	v_and_b32_e32 v173, 0xffff0000, v96
	v_fma_f32 v9, |v128|, s80, 1.0
	v_pk_mul_f32 v[170:171], v[128:129], v[128:129]
	v_rcp_f32_e32 v140, v9
	v_mul_f32_e32 v9, 0xbf38aa3b, v170
	v_exp_f32_e32 v170, v9
	v_fma_f32 v9, |v129|, s80, 1.0
	v_rcp_f32_e32 v141, v9
	v_mul_f32_e32 v9, 0xbf38aa3b, v171
	v_exp_f32_e32 v171, v9
	v_cmp_gt_f32_e32 vcc, 0, v128
	v_pk_fma_f32 v[174:175], v[140:141], s[68:69], v[168:169] op_sel_hi:[1,0,0]
	v_cmp_gt_f32_e64 s[0:1], 0, v129
	v_pk_fma_f32 v[174:175], v[140:141], v[174:175], s[44:45] op_sel_hi:[1,1,0]
	s_nop 0
	v_pk_fma_f32 v[174:175], v[140:141], v[174:175], s[84:85] op_sel_hi:[1,1,0]
	s_nop 0
	v_pk_fma_f32 v[174:175], v[140:141], v[174:175], s[64:65] op_sel_hi:[1,1,0]
	s_nop 0
	v_pk_mul_f32 v[140:141], v[140:141], v[174:175]
	s_nop 0
	v_pk_mul_f32 v[140:141], v[170:171], v[140:141]
	s_nop 0
	v_pk_mul_f32 v[170:171], v[128:129], v[140:141]
	v_pk_fma_f32 v[128:129], v[128:129], v[140:141], v[128:129] neg_lo:[1,0,0] neg_hi:[1,0,0]
	v_lshlrev_b32_e32 v140, 16, v97
	v_cndmask_b32_e64 v129, v129, v171, s[0:1]
	v_cndmask_b32_e32 v128, v128, v170, vcc
	v_pk_mul_f32 v[128:129], v[128:129], v[172:173]
	v_and_b32_e32 v141, 0xffff0000, v97
	v_cvt_pk_bf16_f32 v84, v128, v129
	v_pk_mul_f32 v[128:129], v[14:15], v[142:143]
	s_nop 0
	v_pk_fma_f32 v[128:129], v[6:7], v[146:147], v[128:129]
	v_lshlrev_b32_e32 v146, 16, v89
	v_and_b32_e32 v147, 0xffff0000, v89
	v_pk_fma_f32 v[88:89], v[22:23], v[146:147], v[128:129]
	v_pk_mul_f32 v[128:129], v[30:31], v[160:161]
	v_lshlrev_b32_e32 v160, 16, v85
	v_pk_fma_f32 v[128:129], v[38:39], v[152:153], v[128:129]
	v_and_b32_e32 v161, 0xffff0000, v85
	v_pk_add_f32 v[88:89], v[82:83], v[88:89]
	v_pk_fma_f32 v[128:129], v[46:47], v[160:161], v[128:129]
	s_nop 0
	v_pk_add_f32 v[88:89], v[88:89], v[128:129]
	v_pk_mul_f32 v[128:129], v[54:55], v[158:159]
	v_lshlrev_b32_e32 v158, 16, v93
	v_pk_fma_f32 v[128:129], v[62:63], v[150:151], v[128:129]
	v_and_b32_e32 v159, 0xffff0000, v93
	v_pk_fma_f32 v[92:93], v[70:71], v[158:159], v[128:129]
	s_nop 0
	v_pk_add_f32 v[88:89], v[88:89], v[92:93]
	s_nop 0
	v_fma_f32 v9, |v88|, s80, 1.0
	v_pk_mul_f32 v[128:129], v[88:89], v[88:89]
	v_rcp_f32_e32 v92, v9
	v_mul_f32_e32 v9, 0xbf38aa3b, v128
	v_exp_f32_e32 v96, v9
	v_fma_f32 v9, |v89|, s80, 1.0
	v_rcp_f32_e32 v93, v9
	v_mul_f32_e32 v9, 0xbf38aa3b, v129
	v_exp_f32_e32 v97, v9
	v_cmp_gt_f32_e32 vcc, 0, v88
	v_pk_fma_f32 v[170:171], v[92:93], s[68:69], v[168:169] op_sel_hi:[1,0,0]
	v_cmp_gt_f32_e64 s[0:1], 0, v89
	v_pk_fma_f32 v[170:171], v[92:93], v[170:171], s[44:45] op_sel_hi:[1,1,0]
	v_lshlrev_b32_e32 v128, 16, v90
	v_pk_fma_f32 v[170:171], v[92:93], v[170:171], s[84:85] op_sel_hi:[1,1,0]
	v_and_b32_e32 v129, 0xffff0000, v90
	v_pk_fma_f32 v[170:171], v[92:93], v[170:171], s[64:65] op_sel_hi:[1,1,0]
	s_nop 0
	v_pk_mul_f32 v[92:93], v[92:93], v[170:171]
; __device__ __forceinline__ unsigned pk_bf16(float a, float b) { f32x2 v = {a, b}; bf2_t r = __builtin_convertvector(v, bf2_t); return __builtin_bit_cast(unsigned, r); }
; __device__ __forceinline__ float bf_lo(unsigned u) { return __uint_as_float(u << 16); }
; __device__ __forceinline__ float bf_hi(unsigned u) { return __uint_as_float(u & 0xffff0000u); }
; __device__ void phase_conv(const Params& p, int l, int nrows) {
;     ...
;         for (int i = 0; i < 16; ++i) {
;             const bf16_t* np = gp + (size_t)(i + 1) * FF;
;             const bool v = (c0 + i + 1) < W;
;             R[0] = (v && up) ? *(const u32x4*)(np - (size_t)64 * FF) : zero; R[1] = v ? *(const u32x4*)np : zero; R[2] = (v && dn) ? *(const u32x4*)(np + (size_t)64 * FF) : zero;
;             float acc[8];
; #pragma unroll
;             for (int j = 0; j < 8; ++j) acc[j] = bias[j];
; #pragma unroll
;             for (int rr = 0; rr < 3; ++rr) {
; #pragma unroll
;                 for (int j = 0; j < 4; ++j) {
;                     acc[2 * j] += bf_lo(L[rr][j]) * tp[rr * 3 + 0][2 * j] + bf_lo(M[rr][j]) * tp[rr * 3 + 1][2 * j] + bf_lo(R[rr][j]) * tp[rr * 3 + 2][2 * j];
;                     acc[2 * j + 1] += bf_hi(L[rr][j]) * tp[rr * 3 + 0][2 * j + 1] + bf_hi(M[rr][j]) * tp[rr * 3 + 1][2 * j + 1] + bf_hi(R[rr][j]) * tp[rr * 3 + 2][2 * j + 1];
;                 }
;             }
;             bf16_t* ap = Aup + (size_t)(tok0 + i) * FF + f0;
;             const u32x4 av = __builtin_nontemporal_load((const u32x4*)ap);
;             u32x4 wv;
; #pragma unroll
;             for (int j = 0; j < 4; ++j) wv[j] = pk_bf16(bf_lo(av[j]) * gelu_f(acc[2 * j]), bf_hi(av[j]) * gelu_f(acc[2 * j + 1]));
;             *(u32x4*)ap = wv;
; #pragma unroll
;             for (int rr = 0; rr < 3; ++rr) { L[rr] = M[rr]; M[rr] = R[rr]; }
	s_nop 0
	v_pk_mul_f32 v[92:93], v[96:97], v[92:93]
	s_nop 0
	v_pk_mul_f32 v[96:97], v[88:89], v[92:93]
	v_pk_fma_f32 v[88:89], v[88:89], v[92:93], v[88:89] neg_lo:[1,0,0] neg_hi:[1,0,0]
	v_pk_mul_f32 v[92:93], v[32:33], v[126:127]
	v_cndmask_b32_e64 v89, v89, v97, s[0:1]
	v_cndmask_b32_e32 v88, v88, v96, vcc
	v_pk_mul_f32 v[88:89], v[88:89], v[140:141]
	v_pk_fma_f32 v[92:93], v[40:41], v[112:113], v[92:93]
	v_cvt_pk_bf16_f32 v85, v88, v89
	v_pk_mul_f32 v[88:89], v[16:17], v[100:101]
	v_lshlrev_b32_e32 v140, 16, v86
	v_pk_fma_f32 v[88:89], v[0:1], v[104:105], v[88:89]
	v_and_b32_e32 v141, 0xffff0000, v86
	v_pk_fma_f32 v[88:89], v[24:25], v[128:129], v[88:89]
	v_pk_fma_f32 v[92:93], v[48:49], v[140:141], v[92:93]
	v_pk_add_f32 v[88:89], v[76:77], v[88:89]
	v_lshlrev_b32_e32 v126, 16, v94
	v_pk_add_f32 v[88:89], v[88:89], v[92:93]
	v_pk_mul_f32 v[92:93], v[56:57], v[118:119]
	v_and_b32_e32 v127, 0xffff0000, v94
	v_pk_fma_f32 v[92:93], v[64:65], v[110:111], v[92:93]
	v_lshlrev_b32_e32 v104, 16, v98
	v_pk_fma_f32 v[92:93], v[72:73], v[126:127], v[92:93]
	v_and_b32_e32 v105, 0xffff0000, v98
	v_pk_add_f32 v[88:89], v[88:89], v[92:93]
	v_lshlrev_b32_e32 v94, 16, v99
	v_fma_f32 v9, |v88|, s80, 1.0
	v_pk_mul_f32 v[96:97], v[88:89], v[88:89]
	v_rcp_f32_e32 v92, v9
	v_mul_f32_e32 v9, 0xbf38aa3b, v96
	v_exp_f32_e32 v96, v9
	v_fma_f32 v9, |v89|, s80, 1.0
	v_rcp_f32_e32 v93, v9
	v_mul_f32_e32 v9, 0xbf38aa3b, v97
	v_exp_f32_e32 v97, v9
	v_cmp_gt_f32_e32 vcc, 0, v88
	v_pk_fma_f32 v[118:119], v[92:93], s[68:69], v[168:169] op_sel_hi:[1,0,0]
	v_cmp_gt_f32_e64 s[0:1], 0, v89
	v_pk_fma_f32 v[118:119], v[92:93], v[118:119], s[44:45] op_sel_hi:[1,1,0]
	s_nop 0
	v_pk_fma_f32 v[118:119], v[92:93], v[118:119], s[84:85] op_sel_hi:[1,1,0]
	s_nop 0
	v_pk_fma_f32 v[118:119], v[92:93], v[118:119], s[64:65] op_sel_hi:[1,1,0]
	s_nop 0
	v_pk_mul_f32 v[92:93], v[92:93], v[118:119]
	v_lshlrev_b32_e32 v118, 16, v91
	v_pk_mul_f32 v[92:93], v[96:97], v[92:93]
	v_and_b32_e32 v119, 0xffff0000, v91
	v_pk_mul_f32 v[96:97], v[88:89], v[92:93]
	v_pk_fma_f32 v[88:89], v[88:89], v[92:93], v[88:89] neg_lo:[1,0,0] neg_hi:[1,0,0]
	v_pk_mul_f32 v[90:91], v[34:35], v[116:117]
	v_cndmask_b32_e64 v89, v89, v97, s[0:1]
	v_cndmask_b32_e32 v88, v88, v96, vcc
	v_pk_mul_f32 v[88:89], v[88:89], v[104:105]
	v_pk_fma_f32 v[90:91], v[42:43], v[108:109], v[90:91]
	v_cvt_pk_bf16_f32 v86, v88, v89
	v_pk_mul_f32 v[88:89], v[18:19], v[10:11]
	v_lshlrev_b32_e32 v116, 16, v87
	v_pk_fma_f32 v[88:89], v[2:3], v[102:103], v[88:89]
	v_and_b32_e32 v117, 0xffff0000, v87
	v_pk_fma_f32 v[88:89], v[26:27], v[118:119], v[88:89]
	v_pk_fma_f32 v[90:91], v[50:51], v[116:117], v[90:91]
	v_pk_add_f32 v[88:89], v[78:79], v[88:89]
	s_nop 0
	v_pk_add_f32 v[88:89], v[88:89], v[90:91]
	v_pk_mul_f32 v[90:91], v[58:59], v[114:115]
	v_lshlrev_b32_e32 v114, 16, v95
	v_pk_fma_f32 v[90:91], v[66:67], v[106:107], v[90:91]
	v_and_b32_e32 v115, 0xffff0000, v95
	v_pk_fma_f32 v[90:91], v[74:75], v[114:115], v[90:91]
	v_and_b32_e32 v95, 0xffff0000, v99
	v_pk_add_f32 v[88:89], v[88:89], v[90:91]
	s_nop 0
	v_fma_f32 v9, |v88|, s80, 1.0
	v_pk_mul_f32 v[92:93], v[88:89], v[88:89]
	v_rcp_f32_e32 v90, v9
	v_mul_f32_e32 v9, 0xbf38aa3b, v92
	v_exp_f32_e32 v92, v9
	v_fma_f32 v9, |v89|, s80, 1.0
	v_rcp_f32_e32 v91, v9
	v_mul_f32_e32 v9, 0xbf38aa3b, v93
	v_exp_f32_e32 v93, v9
	v_cmp_gt_f32_e32 vcc, 0, v88
	v_pk_fma_f32 v[96:97], v[90:91], s[68:69], v[168:169] op_sel_hi:[1,0,0]
	v_cmp_gt_f32_e64 s[0:1], 0, v89
	v_pk_fma_f32 v[96:97], v[90:91], v[96:97], s[44:45] op_sel_hi:[1,1,0]
	v_add_u32_e32 v9, -1, v188
	v_pk_fma_f32 v[96:97], v[90:91], v[96:97], s[84:85] op_sel_hi:[1,1,0]
	s_nop 0
	v_pk_fma_f32 v[96:97], v[90:91], v[96:97], s[64:65] op_sel_hi:[1,1,0]
	s_nop 0
	v_pk_mul_f32 v[90:91], v[90:91], v[96:97]
	s_nop 0
	v_pk_mul_f32 v[90:91], v[92:93], v[90:91]
	s_nop 0
	v_pk_mul_f32 v[92:93], v[88:89], v[90:91]
	v_pk_fma_f32 v[88:89], v[88:89], v[90:91], v[88:89] neg_lo:[1,0,0] neg_hi:[1,0,0]
	s_nop 0
	v_cndmask_b32_e64 v89, v89, v93, s[0:1]
	v_cndmask_b32_e32 v88, v88, v92, vcc
	v_pk_mul_f32 v[88:89], v[88:89], v[94:95]
	v_cmp_lt_u32_e64 s[0:1], v9, v187
	v_cvt_pk_bf16_f32 v87, v88, v89
	global_store_dwordx4 v[166:167], v[84:87], off offset:3584
	s_and_b64 s[6:7], s[0:1], s[40:41]
	v_mov_b32_e32 v92, 0
	v_mov_b32_e32 v84, 0
	v_mov_b32_e32 v93, 0
	v_mov_b32_e32 v94, 0
	v_mov_b32_e32 v95, 0
	s_and_saveexec_b64 s[66:67], s[6:7]
	s_cbranch_execz .LBB0_757
	v_add_co_u32_e32 v86, vcc, 0x13a5e000, v124
	s_nop 1
	v_addc_co_u32_e32 v87, vcc, 0, v125, vcc
.LBB0_757:
	s_or_b64 exec, exec, s[66:67]
	v_mov_b32_e32 v85, 0
	v_mov_b32_e32 v86, 0
	v_mov_b32_e32 v87, 0
	v_mov_b32_e32 v88, 0
	v_mov_b32_e32 v89, 0
	v_mov_b32_e32 v90, 0
	v_mov_b32_e32 v91, 0
	s_and_saveexec_b64 s[66:67], s[0:1]
	s_cbranch_execz .LBB0_761
	v_add_co_u32_e32 v84, vcc, 0x13ab6000, v124
	v_mov_b32_e32 v91, 0
	s_nop 0
	v_addc_co_u32_e32 v85, vcc, 0, v125, vcc
	v_mov_b32_e32 v90, 0
	v_mov_b32_e32 v89, 0
	v_mov_b32_e32 v88, 0
	s_and_saveexec_b64 s[0:1], s[42:43]
	s_cbranch_execz .LBB0_760
	v_add_co_u32_e32 v88, vcc, 0x13b0e000, v124
	s_nop 1
	v_addc_co_u32_e32 v89, vcc, 0, v125, vcc

; __device__ __forceinline__ unsigned pk_bf16(float a, float b) { f32x2 v = {a, b}; bf2_t r = __builtin_convertvector(v, bf2_t); return __builtin_bit_cast(unsigned, r); }
; __device__ __forceinline__ float bf_lo(unsigned u) { return __uint_as_float(u << 16); }
; __device__ __forceinline__ float bf_hi(unsigned u) { return __uint_as_float(u & 0xffff0000u); }
; __device__ void phase_conv(const Params& p, int l, int nrows) {
;     ...
;         for (int i = 0; i < 16; ++i) {
;             const bf16_t* np = gp + (size_t)(i + 1) * FF;
;             const bool v = (c0 + i + 1) < W;
;             R[0] = (v && up) ? *(const u32x4*)(np - (size_t)64 * FF) : zero; R[1] = v ? *(const u32x4*)np : zero; R[2] = (v && dn) ? *(const u32x4*)(np + (size_t)64 * FF) : zero;
;             float acc[8];
; #pragma unroll
;             for (int j = 0; j < 8; ++j) acc[j] = bias[j];
; #pragma unroll
;             for (int rr = 0; rr < 3; ++rr) {
; #pragma unroll
;                 for (int j = 0; j < 4; ++j) {
;                     acc[2 * j] += bf_lo(L[rr][j]) * tp[rr * 3 + 0][2 * j] + bf_lo(M[rr][j]) * tp[rr * 3 + 1][2 * j] + bf_lo(R[rr][j]) * tp[rr * 3 + 2][2 * j];
;                     acc[2 * j + 1] += bf_hi(L[rr][j]) * tp[rr * 3 + 0][2 * j + 1] + bf_hi(M[rr][j]) * tp[rr * 3 + 1][2 * j + 1] + bf_hi(R[rr][j]) * tp[rr * 3 + 2][2 * j + 1];
;                 }
;             }
;             bf16_t* ap = Aup + (size_t)(tok0 + i) * FF + f0;
;             const u32x4 av = __builtin_nontemporal_load((const u32x4*)ap);
;             u32x4 wv;
; #pragma unroll
;             for (int j = 0; j < 4; ++j) wv[j] = pk_bf16(bf_lo(av[j]) * gelu_f(acc[2 * j]), bf_hi(av[j]) * gelu_f(acc[2 * j + 1]));
;             *(u32x4*)ap = wv;
; #pragma unroll
;             for (int rr = 0; rr < 3; ++rr) { L[rr] = M[rr]; M[rr] = R[rr]; }
.LBB0_761:
	s_or_b64 exec, exec, s[66:67]
	v_add_co_u32_e32 v102, vcc, 0x7fb5000, v124
	v_pk_mul_f32 v[104:105], v[12:13], v[148:149]
	s_nop 0
	v_addc_co_u32_e32 v103, vcc, 0, v125, vcc
	v_pk_fma_f32 v[104:105], v[4:5], v[144:145], v[104:105]
	s_waitcnt vmcnt(1)
	v_mov_b64_e32 v[92:93], v[200:201]
	v_mov_b64_e32 v[94:95], v[202:203]
	v_mov_b64_e32 v[84:85], v[204:205]
	v_mov_b64_e32 v[86:87], v[206:207]
	v_mov_b64_e32 v[88:89], v[208:209]
	v_mov_b64_e32 v[90:91], v[210:211]
	v_mov_b64_e32 v[96:97], v[196:197]
	v_mov_b64_e32 v[98:99], v[198:199]
	v_add_u32_e32 v214, 0, v188
	v_cmp_lt_u32_e64 s[98:99], v214, v187
	s_add_u32 s100, s20, 0x7fb6a00
	s_addc_u32 s101, s21, 0
	global_load_dwordx4 v[196:199], v192, s[100:101] nt
	v_mov_b32_e32 v200, 0
	v_mov_b32_e32 v201, 0
	v_mov_b32_e32 v202, 0
	v_mov_b32_e32 v203, 0
	v_mov_b32_e32 v204, 0
	v_mov_b32_e32 v205, 0
	v_mov_b32_e32 v206, 0
	v_mov_b32_e32 v207, 0
	v_mov_b32_e32 v208, 0
	v_mov_b32_e32 v209, 0
	v_mov_b32_e32 v210, 0
	v_mov_b32_e32 v211, 0
	s_add_u32 s10, s20, 0x13ab8000
	s_addc_u32 s11, s21, 0
	s_and_saveexec_b64 s[22:23], s[98:99]
	global_load_dwordx4 v[204:207], v192, s[10:11]
	s_add_u32 s100, s20, 0x13a60000
	s_addc_u32 s101, s21, 0
	s_and_b64 exec, exec, s[40:41]
	global_load_dwordx4 v[200:203], v192, s[100:101]
	s_add_u32 s10, s20, 0x13b10000
	s_addc_u32 s11, s21, 0
	s_and_b64 exec, s[22:23], s[98:99]
	s_and_b64 exec, exec, s[42:43]
	global_load_dwordx4 v[208:211], v192, s[10:11]
	s_mov_b64 exec, s[22:23]
	v_lshlrev_b32_e32 v174, 16, v92
	v_and_b32_e32 v175, 0xffff0000, v92
	v_pk_mul_f32 v[144:145], v[28:29], v[156:157]
	v_pk_fma_f32 v[104:105], v[20:21], v[174:175], v[104:105]
	v_pk_fma_f32 v[144:145], v[36:37], v[164:165], v[144:145]
	v_lshlrev_b32_e32 v170, 16, v84
	v_and_b32_e32 v171, 0xffff0000, v84
	v_pk_add_f32 v[104:105], v[80:81], v[104:105]
	v_pk_fma_f32 v[144:145], v[44:45], v[170:171], v[144:145]
	v_lshlrev_b32_e32 v168, 16, v88
	v_pk_add_f32 v[104:105], v[104:105], v[144:145]
	v_pk_mul_f32 v[144:145], v[52:53], v[154:155]
	v_and_b32_e32 v169, 0xffff0000, v88
	v_pk_fma_f32 v[144:145], v[60:61], v[162:163], v[144:145]
	v_pk_mul_f32 v[112:113], v[32:33], v[112:113]
	v_pk_fma_f32 v[144:145], v[68:69], v[168:169], v[144:145]
	v_pk_fma_f32 v[112:113], v[40:41], v[140:141], v[112:113]
	v_pk_add_f32 v[144:145], v[104:105], v[144:145]
	v_mov_b64_e32 v[104:105], s[90:91]
	v_fma_f32 v9, |v144|, s80, 1.0
	v_pk_mul_f32 v[156:157], v[144:145], v[144:145]
	v_rcp_f32_e32 v154, v9
	v_mul_f32_e32 v9, 0xbf38aa3b, v156
	v_exp_f32_e32 v156, v9
	v_fma_f32 v9, |v145|, s80, 1.0
	v_rcp_f32_e32 v155, v9
	v_mul_f32_e32 v9, 0xbf38aa3b, v157
	v_exp_f32_e32 v157, v9
	v_cmp_gt_f32_e32 vcc, 0, v144
	v_pk_fma_f32 v[172:173], v[154:155], s[68:69], v[104:105] op_sel_hi:[1,0,0]
	v_cmp_gt_f32_e64 s[0:1], 0, v145
	v_pk_fma_f32 v[172:173], v[154:155], v[172:173], s[44:45] op_sel_hi:[1,1,0]
	v_pk_mul_f32 v[110:111], v[56:57], v[110:111]
	v_pk_fma_f32 v[172:173], v[154:155], v[172:173], s[84:85] op_sel_hi:[1,1,0]
	v_pk_fma_f32 v[110:111], v[64:65], v[126:127], v[110:111]
	v_pk_fma_f32 v[172:173], v[154:155], v[172:173], s[64:65] op_sel_hi:[1,1,0]
	s_nop 0
	v_lshlrev_b32_e32 v166, 16, v96
	v_pk_mul_f32 v[154:155], v[154:155], v[172:173]
	v_and_b32_e32 v167, 0xffff0000, v96
	v_pk_mul_f32 v[154:155], v[156:157], v[154:155]
	v_lshlrev_b32_e32 v172, 16, v93
	v_pk_mul_f32 v[156:157], v[144:145], v[154:155]
	v_pk_fma_f32 v[144:145], v[144:145], v[154:155], v[144:145] neg_lo:[1,0,0] neg_hi:[1,0,0]
	v_and_b32_e32 v173, 0xffff0000, v93
	v_cndmask_b32_e64 v145, v145, v157, s[0:1]
	v_cndmask_b32_e32 v144, v144, v156, vcc
	v_pk_mul_f32 v[144:145], v[144:145], v[166:167]
	v_lshlrev_b32_e32 v166, 16, v85
	v_cvt_pk_bf16_f32 v96, v144, v145
	v_pk_mul_f32 v[144:145], v[14:15], v[146:147]
	v_and_b32_e32 v167, 0xffff0000, v85
	v_pk_fma_f32 v[142:143], v[6:7], v[142:143], v[144:145]
	v_pk_mul_f32 v[144:145], v[30:31], v[152:153]
	v_pk_fma_f32 v[142:143], v[22:23], v[172:173], v[142:143]
	v_pk_fma_f32 v[144:145], v[38:39], v[160:161], v[144:145]
	v_pk_add_f32 v[142:143], v[82:83], v[142:143]
	v_pk_fma_f32 v[144:145], v[46:47], v[166:167], v[144:145]
	v_lshlrev_b32_e32 v156, 16, v89
	v_pk_add_f32 v[142:143], v[142:143], v[144:145]
	v_pk_mul_f32 v[144:145], v[54:55], v[150:151]
	v_and_b32_e32 v157, 0xffff0000, v89
	v_pk_fma_f32 v[144:145], v[62:63], v[158:159], v[144:145]
	v_lshlrev_b32_e32 v152, 16, v97
	v_pk_fma_f32 v[144:145], v[70:71], v[156:157], v[144:145]
	v_and_b32_e32 v153, 0xffff0000, v97
	v_pk_add_f32 v[142:143], v[142:143], v[144:145]
	s_nop 0
	v_fma_f32 v9, |v142|, s80, 1.0
	v_pk_mul_f32 v[150:151], v[142:143], v[142:143]
	v_rcp_f32_e32 v144, v9
	v_mul_f32_e32 v9, 0xbf38aa3b, v150
	v_exp_f32_e32 v150, v9
	v_fma_f32 v9, |v143|, s80, 1.0
	v_rcp_f32_e32 v145, v9
	v_mul_f32_e32 v9, 0xbf38aa3b, v151
	v_exp_f32_e32 v151, v9
	v_cmp_gt_f32_e32 vcc, 0, v142
	v_pk_fma_f32 v[154:155], v[144:145], s[68:69], v[104:105] op_sel_hi:[1,0,0]
	v_cmp_gt_f32_e64 s[0:1], 0, v143
	v_pk_fma_f32 v[154:155], v[144:145], v[154:155], s[44:45] op_sel_hi:[1,1,0]
	s_nop 0
	v_pk_fma_f32 v[154:155], v[144:145], v[154:155], s[84:85] op_sel_hi:[1,1,0]
	s_nop 0
	v_pk_fma_f32 v[154:155], v[144:145], v[154:155], s[64:65] op_sel_hi:[1,1,0]
	s_nop 0
; __device__ __forceinline__ unsigned pk_bf16(float a, float b) { f32x2 v = {a, b}; bf2_t r = __builtin_convertvector(v, bf2_t); return __builtin_bit_cast(unsigned, r); }
; __device__ __forceinline__ float bf_lo(unsigned u) { return __uint_as_float(u << 16); }
; __device__ __forceinline__ float bf_hi(unsigned u) { return __uint_as_float(u & 0xffff0000u); }
; __device__ void phase_conv(const Params& p, int l, int nrows) {
;     ...
;         for (int i = 0; i < 16; ++i) {
;             const bf16_t* np = gp + (size_t)(i + 1) * FF;
;             const bool v = (c0 + i + 1) < W;
;             R[0] = (v && up) ? *(const u32x4*)(np - (size_t)64 * FF) : zero; R[1] = v ? *(const u32x4*)np : zero; R[2] = (v && dn) ? *(const u32x4*)(np + (size_t)64 * FF) : zero;
;             float acc[8];
; #pragma unroll
;             for (int j = 0; j < 8; ++j) acc[j] = bias[j];
; #pragma unroll
;             for (int rr = 0; rr < 3; ++rr) {
; #pragma unroll
;                 for (int j = 0; j < 4; ++j) {
;                     acc[2 * j] += bf_lo(L[rr][j]) * tp[rr * 3 + 0][2 * j] + bf_lo(M[rr][j]) * tp[rr * 3 + 1][2 * j] + bf_lo(R[rr][j]) * tp[rr * 3 + 2][2 * j];
;                     acc[2 * j + 1] += bf_hi(L[rr][j]) * tp[rr * 3 + 0][2 * j + 1] + bf_hi(M[rr][j]) * tp[rr * 3 + 1][2 * j + 1] + bf_hi(R[rr][j]) * tp[rr * 3 + 2][2 * j + 1];
;                 }
;             }
;             bf16_t* ap = Aup + (size_t)(tok0 + i) * FF + f0;
;             const u32x4 av = __builtin_nontemporal_load((const u32x4*)ap);
;             u32x4 wv;
; #pragma unroll
;             for (int j = 0; j < 4; ++j) wv[j] = pk_bf16(bf_lo(av[j]) * gelu_f(acc[2 * j]), bf_hi(av[j]) * gelu_f(acc[2 * j + 1]));
;             *(u32x4*)ap = wv;
; #pragma unroll
;             for (int rr = 0; rr < 3; ++rr) { L[rr] = M[rr]; M[rr] = R[rr]; }
	v_pk_mul_f32 v[144:145], v[144:145], v[154:155]
	v_lshlrev_b32_e32 v154, 16, v94
	v_pk_mul_f32 v[144:145], v[150:151], v[144:145]
	v_and_b32_e32 v155, 0xffff0000, v94
	v_pk_mul_f32 v[150:151], v[142:143], v[144:145]
	v_pk_fma_f32 v[142:143], v[142:143], v[144:145], v[142:143] neg_lo:[1,0,0] neg_hi:[1,0,0]
	v_lshlrev_b32_e32 v144, 16, v90
	v_cndmask_b32_e64 v143, v143, v151, s[0:1]
	v_cndmask_b32_e32 v142, v142, v150, vcc
	v_pk_mul_f32 v[142:143], v[142:143], v[152:153]
	v_lshlrev_b32_e32 v150, 16, v86
	v_cvt_pk_bf16_f32 v97, v142, v143
	v_pk_mul_f32 v[142:143], v[16:17], v[128:129]
	v_and_b32_e32 v151, 0xffff0000, v86
	v_pk_fma_f32 v[100:101], v[0:1], v[100:101], v[142:143]
	v_pk_fma_f32 v[112:113], v[48:49], v[150:151], v[112:113]
	v_pk_fma_f32 v[100:101], v[24:25], v[154:155], v[100:101]
	v_and_b32_e32 v145, 0xffff0000, v90
	v_pk_add_f32 v[100:101], v[76:77], v[100:101]
	v_pk_fma_f32 v[110:111], v[72:73], v[144:145], v[110:111]
	v_pk_add_f32 v[100:101], v[100:101], v[112:113]
	v_lshlrev_b32_e32 v142, 16, v98
	v_pk_add_f32 v[100:101], v[100:101], v[110:111]
	v_and_b32_e32 v143, 0xffff0000, v98
	v_fma_f32 v9, |v100|, s80, 1.0
	v_pk_mul_f32 v[112:113], v[100:101], v[100:101]
	v_rcp_f32_e32 v110, v9
	v_mul_f32_e32 v9, 0xbf38aa3b, v112
	v_exp_f32_e32 v112, v9
	v_fma_f32 v9, |v101|, s80, 1.0
	v_rcp_f32_e32 v111, v9
	v_mul_f32_e32 v9, 0xbf38aa3b, v113
	v_exp_f32_e32 v113, v9
	v_cmp_gt_f32_e32 vcc, 0, v100
	v_pk_fma_f32 v[152:153], v[110:111], s[68:69], v[104:105] op_sel_hi:[1,0,0]
	v_cmp_gt_f32_e64 s[0:1], 0, v101
	v_pk_fma_f32 v[152:153], v[110:111], v[152:153], s[44:45] op_sel_hi:[1,1,0]
	s_nop 0
	v_pk_fma_f32 v[152:153], v[110:111], v[152:153], s[84:85] op_sel_hi:[1,1,0]
	s_nop 0
	v_pk_fma_f32 v[152:153], v[110:111], v[152:153], s[64:65] op_sel_hi:[1,1,0]
	s_nop 0
	v_pk_mul_f32 v[110:111], v[110:111], v[152:153]
	v_lshlrev_b32_e32 v152, 16, v95
	v_pk_mul_f32 v[110:111], v[112:113], v[110:111]
	v_and_b32_e32 v153, 0xffff0000, v95
	v_pk_mul_f32 v[112:113], v[100:101], v[110:111]
	v_pk_fma_f32 v[100:101], v[100:101], v[110:111], v[100:101] neg_lo:[1,0,0] neg_hi:[1,0,0]
	s_nop 0
	v_cndmask_b32_e64 v101, v101, v113, s[0:1]
	v_cndmask_b32_e32 v100, v100, v112, vcc
	v_pk_mul_f32 v[100:101], v[100:101], v[142:143]
	v_lshlrev_b32_e32 v142, 16, v87
	v_cvt_pk_bf16_f32 v98, v100, v101
	v_pk_mul_f32 v[100:101], v[18:19], v[118:119]
	v_and_b32_e32 v143, 0xffff0000, v87
	v_pk_fma_f32 v[10:11], v[2:3], v[10:11], v[100:101]
	v_pk_mul_f32 v[100:101], v[34:35], v[108:109]
	v_pk_fma_f32 v[10:11], v[26:27], v[152:153], v[10:11]
	v_pk_fma_f32 v[100:101], v[42:43], v[116:117], v[100:101]
	v_pk_add_f32 v[10:11], v[78:79], v[10:11]
	v_pk_fma_f32 v[100:101], v[50:51], v[142:143], v[100:101]
	v_lshlrev_b32_e32 v112, 16, v91
	v_pk_add_f32 v[10:11], v[10:11], v[100:101]
	v_pk_mul_f32 v[100:101], v[58:59], v[106:107]
	v_and_b32_e32 v113, 0xffff0000, v91
	v_pk_fma_f32 v[100:101], v[66:67], v[114:115], v[100:101]
	v_lshlrev_b32_e32 v108, 16, v99
	v_pk_fma_f32 v[100:101], v[74:75], v[112:113], v[100:101]
	v_and_b32_e32 v109, 0xffff0000, v99
	v_pk_add_f32 v[10:11], v[10:11], v[100:101]
	s_nop 0
	v_fma_f32 v9, |v10|, s80, 1.0
	v_pk_mul_f32 v[106:107], v[10:11], v[10:11]
	v_rcp_f32_e32 v100, v9
	v_mul_f32_e32 v9, 0xbf38aa3b, v106
	v_exp_f32_e32 v106, v9
	v_fma_f32 v9, |v11|, s80, 1.0
	v_rcp_f32_e32 v101, v9
	v_mul_f32_e32 v9, 0xbf38aa3b, v107
	v_exp_f32_e32 v107, v9
	v_cmp_gt_f32_e32 vcc, 0, v10
	v_pk_fma_f32 v[104:105], v[100:101], s[68:69], v[104:105] op_sel_hi:[1,0,0]
	v_cmp_gt_f32_e64 s[0:1], 0, v11
	v_pk_fma_f32 v[104:105], v[100:101], v[104:105], s[44:45] op_sel_hi:[1,1,0]
	s_nop 0
	v_pk_fma_f32 v[104:105], v[100:101], v[104:105], s[84:85] op_sel_hi:[1,1,0]
	s_nop 0
	v_pk_fma_f32 v[104:105], v[100:101], v[104:105], s[64:65] op_sel_hi:[1,1,0]
	s_nop 0
	v_pk_mul_f32 v[100:101], v[100:101], v[104:105]
	s_nop 0
	v_pk_mul_f32 v[100:101], v[106:107], v[100:101]
	v_mov_b32_e32 v106, 0
	v_pk_mul_f32 v[104:105], v[10:11], v[100:101]
	v_pk_fma_f32 v[10:11], v[10:11], v[100:101], v[10:11] neg_lo:[1,0,0] neg_hi:[1,0,0]
	v_mov_b32_e32 v107, 0
	v_cndmask_b32_e64 v11, v11, v105, s[0:1]
	v_cndmask_b32_e32 v10, v10, v104, vcc
	v_pk_mul_f32 v[10:11], v[10:11], v[108:109]
	v_cmp_lt_u32_e64 s[0:1], v188, v187
	v_cvt_pk_bf16_f32 v99, v10, v11
	global_store_dwordx4 v[102:103], v[96:99], off offset:1024
	s_and_b64 s[6:7], s[0:1], s[40:41]
	v_mov_b32_e32 v104, 0
	v_mov_b32_e32 v96, 0
	v_mov_b32_e32 v105, 0
	s_and_saveexec_b64 s[66:67], s[6:7]
	s_cbranch_execz .LBB0_763
	v_add_co_u32_e32 v10, vcc, 0x13a60000, v124
	s_nop 1
	v_addc_co_u32_e32 v11, vcc, 0, v125, vcc
.LBB0_763:
	s_or_b64 exec, exec, s[66:67]
	v_mov_b32_e32 v10, v8
	v_mov_b32_e32 v11, v8
	v_mov_b32_e32 v9, v8
	v_mov_b64_e32 v[102:103], v[10:11]
	v_mov_b64_e32 v[100:101], v[8:9]
	v_mov_b32_e32 v97, 0
	v_mov_b32_e32 v98, 0
	v_mov_b32_e32 v99, 0
	s_and_saveexec_b64 s[66:67], s[0:1]
	s_cbranch_execz .LBB0_718
	v_add_co_u32_e32 v10, vcc, 0x13ab8000, v124
	v_mov_b32_e32 v99, 0
	s_nop 0
	v_addc_co_u32_e32 v11, vcc, 0, v125, vcc
	v_mov_b32_e32 v98, 0
	v_mov_b32_e32 v97, 0
	v_mov_b32_e32 v96, 0
	s_and_saveexec_b64 s[0:1], s[42:43]
	s_cbranch_execz .LBB0_717
	v_add_co_u32_e32 v10, vcc, 0x13b10000, v124
	s_nop 1
	v_addc_co_u32_e32 v11, vcc, 0, v125, vcc
	s_branch .LBB0_717
